# combined: conv 32-deep loads + batched LDS readback, mixer waitcnt relaxations, GEMM prio raised before barrier and redundant lgkmcnt dropped
# speedup vs baseline: 1.0141x; 1.0098x over previous
; #define PG8_STAGE(bufoff, gbase, voff) do { _Pragma("unroll") for (int _i = 0; _i < 2; ++_i) \
;         __builtin_amdgcn_global_load_lds((const unsigned*)((const char*)(gbase) + (voff)[_i]), (PG8_LAS unsigned*)(lds + (bufoff) + ldsw + _i * 8192), 16, 0, 0); } while (0)
; #define PG8_LDA(dst, b, h) do { _Pragma("unroll") for (int m = 0; m < 4; ++m) _Pragma("unroll") for (int k = 0; k < 2; ++k) dst[m][k] = *(const PG8_LAS bf16x8*)(lds + PG8_SA(b, h) + aoff + m * 2048 + k * 1024); } while (0)
; #define PG8_LDB(dst, b, h) do { _Pragma("unroll") for (int n = 0; n < 2; ++n) _Pragma("unroll") for (int k = 0; k < 2; ++k) dst[n][k] = *(const PG8_LAS bf16x8*)(lds + PG8_SB(b, h) + boff + n * 2048 + k * 1024); } while (0)
; #define PG8_MMA(ai, bj, At, Bt) do { __builtin_amdgcn_s_setprio(1); _Pragma("unroll") for (int m = 0; m < 4; ++m) _Pragma("unroll") for (int n = 0; n < 2; ++n) _Pragma("unroll") for (int k = 0; k < 2; ++k) \
;         acc[ai][bj][m][n] = __builtin_amdgcn_mfma_f32_16x16x32_bf16(Bt[n][k], At[m][k], acc[ai][bj][m][n], 0, 0, 0); __builtin_amdgcn_s_setprio(0); } while (0)
; #define PG8_WAIT_V(n) asm volatile("s_waitcnt vmcnt(" #n ")" ::: "memory")
; #define PG8_WAIT_L(n) asm volatile("s_waitcnt lgkmcnt(" #n ")" ::: "memory")
; template <class Epi, class Sched, bool ALIGN_EPI = false, bool SP2 = false>
; __device__ __forceinline__ void gemm_phase(PG8_LAS unsigned char* lds, const Gemm g, const Sched& S, const Epi& E, const int tid) {
;     ...
;             const char* a2 = last ? nA : cA + (size_t)(t + 2) * kstep; const char* b2 = last ? nB : cB + (size_t)(t + 2) * kstep;
;             const char* a3 = a2 + kstep; const char* b3 = b2 + kstep;
;             if (last && has_next) S.a_ready(nxt);
;             if (last) E.prefetch(lds + EPI_LDS_OFF + wid * 1024, cur, wr, wc, lane);
;             if constexpr (SP2) {
;             PG8_LDB(B0, 0, 0); PG8_LDB(B1, 0, 1); PG8_SCHED; PG8_LDA(At, 0, 0); PG8_STAGE(PG8_SA(1, 1), a1 + hstep, voffA);
;             PG8_WAIT_V(8); PG8_WAIT_L(0); PG8_BAR; PG8_MMA(0, 0, At, B0); PG8_MMA(0, 1, At, B1); PG8_BAR; PG8_SCHED;
;             PG8_LDA(At, 0, 1); PG8_STAGE(PG8_SB(0, 0), b2, voffB); PG8_STAGE(PG8_SB(0, 1), b2 + hstep, voffB); PG8_STAGE(PG8_SA(0, 0), a2, voffA);
;             PG8_WAIT_V(8); PG8_WAIT_L(0); PG8_BAR; PG8_MMA(1, 0, At, B0); PG8_MMA(1, 1, At, B1); PG8_BAR; PG8_SCHED;
.LBB0_42:
	s_add_u32 s18, s16, 0x100
	s_addc_u32 s19, s17, 0
	s_and_b64 s[20:21], s[20:21], exec
	s_cselect_b32 s23, s9, s19
	s_cselect_b32 s22, s8, s18
	s_cselect_b32 s21, s15, s74
	s_cselect_b32 s20, s14, s55
	s_add_i32 s3, 0, 0x10000
	s_add_i32 s42, 0, 0x14000
	v_add_u32_e32 v146, s3, v224
	v_add_u32_e32 v162, s42, v224
	ds_read_b128 v[134:137], v146
	ds_read_b128 v[138:141], v146 offset:1024
	ds_read_b128 v[142:145], v146 offset:2048
	ds_read_b128 v[146:149], v146 offset:3072
	ds_read_b128 v[150:153], v162
	ds_read_b128 v[154:157], v162 offset:1024
	ds_read_b128 v[158:161], v162 offset:2048
	ds_read_b128 v[172:175], v162 offset:3072
	v_lshl_add_u64 v[162:163], s[16:17], 0, v[168:169]
	s_add_i32 m0, s27, 0xc000
	ds_read_b128 v[176:179], v228
	ds_read_b128 v[180:183], v228 offset:1024
	ds_read_b128 v[186:189], v228 offset:2048
	ds_read_b128 v[190:193], v228 offset:3072
	ds_read_b128 v[194:197], v228 offset:4096
	ds_read_b128 v[198:201], v228 offset:5120
	ds_read_b128 v[202:205], v228 offset:6144
	ds_read_b128 v[206:209], v228 offset:7168
	global_load_lds_dwordx4 v[162:163], off
	v_lshl_add_u64 v[162:163], s[16:17], 0, v[170:171]
	s_add_i32 m0, s27, 0xe000
	s_nop 0
	global_load_lds_dwordx4 v[162:163], off
	s_waitcnt vmcnt(8)
	s_waitcnt lgkmcnt(0)
	s_setprio 1
	s_barrier
	v_mfma_f32_16x16x32_bf16 v[128:131], v[134:137], v[176:179], v[128:131]
	v_mfma_f32_16x16x32_bf16 v[124:127], v[142:145], v[176:179], v[124:127]
	v_mfma_f32_16x16x32_bf16 v[112:115], v[134:137], v[186:189], v[112:115]
	v_mfma_f32_16x16x32_bf16 v[108:111], v[142:145], v[186:189], v[108:111]
	v_mfma_f32_16x16x32_bf16 v[96:99], v[134:137], v[194:197], v[96:99]
	v_mfma_f32_16x16x32_bf16 v[92:95], v[142:145], v[194:197], v[92:95]
	v_mfma_f32_16x16x32_bf16 v[80:83], v[134:137], v[202:205], v[80:83]
	v_mfma_f32_16x16x32_bf16 v[76:79], v[142:145], v[202:205], v[76:79]
	v_mfma_f32_16x16x32_bf16 v[128:131], v[138:141], v[180:183], v[128:131]
	v_mfma_f32_16x16x32_bf16 v[124:127], v[146:149], v[180:183], v[124:127]
	v_mfma_f32_16x16x32_bf16 v[112:115], v[138:141], v[190:193], v[112:115]
	v_mfma_f32_16x16x32_bf16 v[108:111], v[146:149], v[190:193], v[108:111]
	v_mfma_f32_16x16x32_bf16 v[96:99], v[138:141], v[198:201], v[96:99]
	v_mfma_f32_16x16x32_bf16 v[92:95], v[146:149], v[198:201], v[92:95]
	v_mfma_f32_16x16x32_bf16 v[80:83], v[138:141], v[206:209], v[80:83]
	v_mfma_f32_16x16x32_bf16 v[76:79], v[146:149], v[206:209], v[76:79]
	s_setprio 0
	s_setprio 1
	v_mfma_f32_16x16x32_bf16 v[120:123], v[150:153], v[176:179], v[120:123]
	v_mfma_f32_16x16x32_bf16 v[116:119], v[158:161], v[176:179], v[116:119]
	v_mfma_f32_16x16x32_bf16 v[104:107], v[150:153], v[186:189], v[104:107]
	v_mfma_f32_16x16x32_bf16 v[100:103], v[158:161], v[186:189], v[100:103]
	v_mfma_f32_16x16x32_bf16 v[88:91], v[150:153], v[194:197], v[88:91]
	v_mfma_f32_16x16x32_bf16 v[84:87], v[158:161], v[194:197], v[84:87]
	v_mfma_f32_16x16x32_bf16 v[72:75], v[150:153], v[202:205], v[72:75]
	v_mfma_f32_16x16x32_bf16 v[68:71], v[158:161], v[202:205], v[68:71]
	v_mfma_f32_16x16x32_bf16 v[120:123], v[154:157], v[180:183], v[120:123]
	v_mfma_f32_16x16x32_bf16 v[116:119], v[172:175], v[180:183], v[116:119]
	v_mfma_f32_16x16x32_bf16 v[104:107], v[154:157], v[190:193], v[104:107]
	v_mfma_f32_16x16x32_bf16 v[100:103], v[172:175], v[190:193], v[100:103]
	v_mfma_f32_16x16x32_bf16 v[88:91], v[154:157], v[198:201], v[88:91]
	v_mfma_f32_16x16x32_bf16 v[84:87], v[172:175], v[198:201], v[84:87]
	v_mfma_f32_16x16x32_bf16 v[72:75], v[154:157], v[206:209], v[72:75]
	v_mfma_f32_16x16x32_bf16 v[68:71], v[172:175], v[206:209], v[68:71]
	s_setprio 0
	s_barrier
	s_add_i32 s3, s3, s26
	v_lshl_add_u64 v[162:163], s[20:21], 0, v[2:3]
	s_mov_b32 m0, s3
	ds_read_b128 v[176:179], v228 offset:16384
	ds_read_b128 v[180:183], v228 offset:17408
	ds_read_b128 v[186:189], v228 offset:18432
	ds_read_b128 v[190:193], v228 offset:19456
	ds_read_b128 v[194:197], v228 offset:20480
	ds_read_b128 v[198:201], v228 offset:21504
	ds_read_b128 v[202:205], v228 offset:22528
	ds_read_b128 v[206:209], v228 offset:23552
	global_load_lds_dwordx4 v[162:163], off
	s_add_i32 m0, s3, 0x2000
	s_add_u32 s16, s20, 0x160000
	v_lshl_add_u64 v[210:211], s[20:21], 0, v[166:167]
	s_addc_u32 s17, s21, 0
	s_add_i32 s3, s42, s26
	global_load_lds_dwordx4 v[210:211], off
	v_lshl_add_u64 v[212:213], s[16:17], 0, v[2:3]
	s_mov_b32 m0, s3
	v_lshl_add_u64 v[214:215], s[22:23], 0, v[164:165]
	global_load_lds_dwordx4 v[212:213], off
	v_lshl_add_u64 v[212:213], s[16:17], 0, v[166:167]
	s_add_i32 m0, s3, 0x2000
	s_nop 0
	global_load_lds_dwordx4 v[212:213], off
	v_lshl_add_u64 v[212:213], s[22:23], 0, v[0:1]
	s_mov_b32 m0, s27
	s_nop 0
	global_load_lds_dwordx4 v[212:213], off
	s_mov_b32 m0, s28
	s_nop 0
	global_load_lds_dwordx4 v[214:215], off
	s_waitcnt vmcnt(8)
	s_waitcnt lgkmcnt(0)
	s_setprio 1
	s_barrier
; #define PG8_STAGE(bufoff, gbase, voff) do { _Pragma("unroll") for (int _i = 0; _i < 2; ++_i) \
;         __builtin_amdgcn_global_load_lds((const unsigned*)((const char*)(gbase) + (voff)[_i]), (PG8_LAS unsigned*)(lds + (bufoff) + ldsw + _i * 8192), 16, 0, 0); } while (0)
; #define PG8_LDA(dst, b, h) do { _Pragma("unroll") for (int m = 0; m < 4; ++m) _Pragma("unroll") for (int k = 0; k < 2; ++k) dst[m][k] = *(const PG8_LAS bf16x8*)(lds + PG8_SA(b, h) + aoff + m * 2048 + k * 1024); } while (0)
; #define PG8_LDB(dst, b, h) do { _Pragma("unroll") for (int n = 0; n < 2; ++n) _Pragma("unroll") for (int k = 0; k < 2; ++k) dst[n][k] = *(const PG8_LAS bf16x8*)(lds + PG8_SB(b, h) + boff + n * 2048 + k * 1024); } while (0)
; #define PG8_MMA(ai, bj, At, Bt) do { __builtin_amdgcn_s_setprio(1); _Pragma("unroll") for (int m = 0; m < 4; ++m) _Pragma("unroll") for (int n = 0; n < 2; ++n) _Pragma("unroll") for (int k = 0; k < 2; ++k) \
;         acc[ai][bj][m][n] = __builtin_amdgcn_mfma_f32_16x16x32_bf16(Bt[n][k], At[m][k], acc[ai][bj][m][n], 0, 0, 0); __builtin_amdgcn_s_setprio(0); } while (0)
; #define PG8_WAIT_V(n) asm volatile("s_waitcnt vmcnt(" #n ")" ::: "memory")
; #define PG8_WAIT_L(n) asm volatile("s_waitcnt lgkmcnt(" #n ")" ::: "memory")
; #define PG8_BAR __builtin_amdgcn_s_barrier()
; #define PG8_SCHED __builtin_amdgcn_sched_barrier(0)
; template <class Epi, class Sched, bool ALIGN_EPI = false, bool SP2 = false>
; __device__ __forceinline__ void gemm_phase(PG8_LAS unsigned char* lds, const Gemm g, const Sched& S, const Epi& E, const int tid) {
;     ...
;             PG8_WAIT_V(8); PG8_WAIT_L(0); PG8_BAR; PG8_MMA(1, 0, At, B0); PG8_MMA(1, 1, At, B1); PG8_BAR; PG8_SCHED;
;             PG8_LDB(B0, 1, 0); PG8_LDB(B1, 1, 1); PG8_SCHED; PG8_LDA(At, 1, 0); PG8_STAGE(PG8_SA(0, 1), a2 + hstep, voffA);
;             PG8_WAIT_V(8); PG8_WAIT_L(0); PG8_BAR; PG8_MMA(0, 0, At, B0); PG8_MMA(0, 1, At, B1); PG8_BAR; PG8_SCHED;
	v_mfma_f32_16x16x32_bf16 v[64:67], v[134:137], v[176:179], v[64:67]
	v_mfma_f32_16x16x32_bf16 v[60:63], v[142:145], v[176:179], v[60:63]
	v_mfma_f32_16x16x32_bf16 v[48:51], v[134:137], v[186:189], v[48:51]
	v_mfma_f32_16x16x32_bf16 v[44:47], v[142:145], v[186:189], v[44:47]
	v_mfma_f32_16x16x32_bf16 v[32:35], v[134:137], v[194:197], v[32:35]
	v_mfma_f32_16x16x32_bf16 v[28:31], v[142:145], v[194:197], v[28:31]
	v_mfma_f32_16x16x32_bf16 v[16:19], v[134:137], v[202:205], v[16:19]
	v_mfma_f32_16x16x32_bf16 v[12:15], v[142:145], v[202:205], v[12:15]
	v_mfma_f32_16x16x32_bf16 v[64:67], v[138:141], v[180:183], v[64:67]
	v_mfma_f32_16x16x32_bf16 v[60:63], v[146:149], v[180:183], v[60:63]
	v_mfma_f32_16x16x32_bf16 v[48:51], v[138:141], v[190:193], v[48:51]
	v_mfma_f32_16x16x32_bf16 v[44:47], v[146:149], v[190:193], v[44:47]
	v_mfma_f32_16x16x32_bf16 v[32:35], v[138:141], v[198:201], v[32:35]
	v_mfma_f32_16x16x32_bf16 v[28:31], v[146:149], v[198:201], v[28:31]
	v_mfma_f32_16x16x32_bf16 v[16:19], v[138:141], v[206:209], v[16:19]
	v_mfma_f32_16x16x32_bf16 v[12:15], v[146:149], v[206:209], v[12:15]
	s_setprio 0
	s_setprio 1
	v_mfma_f32_16x16x32_bf16 v[56:59], v[150:153], v[176:179], v[56:59]
	v_mfma_f32_16x16x32_bf16 v[52:55], v[158:161], v[176:179], v[52:55]
	v_mfma_f32_16x16x32_bf16 v[40:43], v[150:153], v[186:189], v[40:43]
	v_mfma_f32_16x16x32_bf16 v[36:39], v[158:161], v[186:189], v[36:39]
	v_mfma_f32_16x16x32_bf16 v[24:27], v[150:153], v[194:197], v[24:27]
	v_mfma_f32_16x16x32_bf16 v[20:23], v[158:161], v[194:197], v[20:23]
	v_mfma_f32_16x16x32_bf16 v[8:11], v[150:153], v[202:205], v[8:11]
	v_mfma_f32_16x16x32_bf16 v[4:7], v[158:161], v[202:205], v[4:7]
	v_mfma_f32_16x16x32_bf16 v[56:59], v[154:157], v[180:183], v[56:59]
	v_mfma_f32_16x16x32_bf16 v[52:55], v[172:175], v[180:183], v[52:55]
	v_mfma_f32_16x16x32_bf16 v[40:43], v[154:157], v[190:193], v[40:43]
	v_mfma_f32_16x16x32_bf16 v[36:39], v[172:175], v[190:193], v[36:39]
	v_mfma_f32_16x16x32_bf16 v[24:27], v[154:157], v[198:201], v[24:27]
	v_mfma_f32_16x16x32_bf16 v[20:23], v[172:175], v[198:201], v[20:23]
	v_mfma_f32_16x16x32_bf16 v[8:11], v[154:157], v[206:209], v[8:11]
	v_mfma_f32_16x16x32_bf16 v[4:7], v[172:175], v[206:209], v[4:7]
	s_setprio 0
	s_barrier
	s_add_i32 s3, 0, 0x18000
	s_add_i32 s42, 0, 0x1c000
	v_add_u32_e32 v146, s3, v224
	v_add_u32_e32 v172, s42, v224
	ds_read_b128 v[134:137], v146
	ds_read_b128 v[138:141], v146 offset:1024
	ds_read_b128 v[142:145], v146 offset:2048
	ds_read_b128 v[146:149], v146 offset:3072
	ds_read_b128 v[150:153], v172
	ds_read_b128 v[154:157], v172 offset:1024
	ds_read_b128 v[158:161], v172 offset:2048
	ds_read_b128 v[172:175], v172 offset:3072
	s_add_u32 s16, s22, 0x160000
	s_addc_u32 s17, s23, 0
	s_mov_b32 m0, s29
	v_lshl_add_u64 v[216:217], s[16:17], 0, v[0:1]
	ds_read_b128 v[176:179], v228 offset:32768
	ds_read_b128 v[180:183], v228 offset:33792
	ds_read_b128 v[186:189], v228 offset:34816
	ds_read_b128 v[190:193], v228 offset:35840
	ds_read_b128 v[194:197], v228 offset:36864
	ds_read_b128 v[198:201], v228 offset:37888
	ds_read_b128 v[202:205], v228 offset:38912
	ds_read_b128 v[206:209], v228 offset:39936
	global_load_lds_dwordx4 v[216:217], off
	v_lshl_add_u64 v[216:217], s[16:17], 0, v[164:165]
	s_mov_b32 m0, s30
	s_nop 0
	global_load_lds_dwordx4 v[216:217], off
	s_waitcnt vmcnt(8)
	s_waitcnt lgkmcnt(0)
	s_setprio 1
	s_barrier
	v_mfma_f32_16x16x32_bf16 v[128:131], v[134:137], v[176:179], v[128:131]
	v_mfma_f32_16x16x32_bf16 v[124:127], v[142:145], v[176:179], v[124:127]
	v_mfma_f32_16x16x32_bf16 v[112:115], v[134:137], v[186:189], v[112:115]
	v_mfma_f32_16x16x32_bf16 v[108:111], v[142:145], v[186:189], v[108:111]
	v_mfma_f32_16x16x32_bf16 v[96:99], v[134:137], v[194:197], v[96:99]
	v_mfma_f32_16x16x32_bf16 v[92:95], v[142:145], v[194:197], v[92:95]
	v_mfma_f32_16x16x32_bf16 v[80:83], v[134:137], v[202:205], v[80:83]
	v_mfma_f32_16x16x32_bf16 v[76:79], v[142:145], v[202:205], v[76:79]
	v_mfma_f32_16x16x32_bf16 v[128:131], v[138:141], v[180:183], v[128:131]
	v_mfma_f32_16x16x32_bf16 v[124:127], v[146:149], v[180:183], v[124:127]
	v_mfma_f32_16x16x32_bf16 v[112:115], v[138:141], v[190:193], v[112:115]
	v_mfma_f32_16x16x32_bf16 v[108:111], v[146:149], v[190:193], v[108:111]
	v_mfma_f32_16x16x32_bf16 v[96:99], v[138:141], v[198:201], v[96:99]
	v_mfma_f32_16x16x32_bf16 v[92:95], v[146:149], v[198:201], v[92:95]
	v_mfma_f32_16x16x32_bf16 v[80:83], v[138:141], v[206:209], v[80:83]
	v_mfma_f32_16x16x32_bf16 v[76:79], v[146:149], v[206:209], v[76:79]
	s_setprio 0
	s_setprio 1
	v_mfma_f32_16x16x32_bf16 v[120:123], v[150:153], v[176:179], v[120:123]
	v_mfma_f32_16x16x32_bf16 v[116:119], v[158:161], v[176:179], v[116:119]
	v_mfma_f32_16x16x32_bf16 v[104:107], v[150:153], v[186:189], v[104:107]
	v_mfma_f32_16x16x32_bf16 v[100:103], v[158:161], v[186:189], v[100:103]
	v_mfma_f32_16x16x32_bf16 v[88:91], v[150:153], v[194:197], v[88:91]
	v_mfma_f32_16x16x32_bf16 v[84:87], v[158:161], v[194:197], v[84:87]
	v_mfma_f32_16x16x32_bf16 v[72:75], v[150:153], v[202:205], v[72:75]
	v_mfma_f32_16x16x32_bf16 v[68:71], v[158:161], v[202:205], v[68:71]
	v_mfma_f32_16x16x32_bf16 v[120:123], v[154:157], v[180:183], v[120:123]
	v_mfma_f32_16x16x32_bf16 v[116:119], v[172:175], v[180:183], v[116:119]
	v_mfma_f32_16x16x32_bf16 v[104:107], v[154:157], v[190:193], v[104:107]
	v_mfma_f32_16x16x32_bf16 v[100:103], v[172:175], v[190:193], v[100:103]
	v_mfma_f32_16x16x32_bf16 v[88:91], v[154:157], v[198:201], v[88:91]
	v_mfma_f32_16x16x32_bf16 v[84:87], v[172:175], v[198:201], v[84:87]
	v_mfma_f32_16x16x32_bf16 v[72:75], v[154:157], v[206:209], v[72:75]
	v_mfma_f32_16x16x32_bf16 v[68:71], v[172:175], v[206:209], v[68:71]
	s_setprio 0
	s_barrier
; #define PG8_STAGE(bufoff, gbase, voff) do { _Pragma("unroll") for (int _i = 0; _i < 2; ++_i) \
;         __builtin_amdgcn_global_load_lds((const unsigned*)((const char*)(gbase) + (voff)[_i]), (PG8_LAS unsigned*)(lds + (bufoff) + ldsw + _i * 8192), 16, 0, 0); } while (0)
; #define PG8_LDA(dst, b, h) do { _Pragma("unroll") for (int m = 0; m < 4; ++m) _Pragma("unroll") for (int k = 0; k < 2; ++k) dst[m][k] = *(const PG8_LAS bf16x8*)(lds + PG8_SA(b, h) + aoff + m * 2048 + k * 1024); } while (0)
; #define PG8_MMA(ai, bj, At, Bt) do { __builtin_amdgcn_s_setprio(1); _Pragma("unroll") for (int m = 0; m < 4; ++m) _Pragma("unroll") for (int n = 0; n < 2; ++n) _Pragma("unroll") for (int k = 0; k < 2; ++k) \
;         acc[ai][bj][m][n] = __builtin_amdgcn_mfma_f32_16x16x32_bf16(Bt[n][k], At[m][k], acc[ai][bj][m][n], 0, 0, 0); __builtin_amdgcn_s_setprio(0); } while (0)
; #define PG8_WAIT_V(n) asm volatile("s_waitcnt vmcnt(" #n ")" ::: "memory")
; #define PG8_WAIT_L(n) asm volatile("s_waitcnt lgkmcnt(" #n ")" ::: "memory")
; #define PG8_BAR __builtin_amdgcn_s_barrier()
; #define PG8_SCHED __builtin_amdgcn_sched_barrier(0)
; template <class Epi, class Sched, bool ALIGN_EPI = false, bool SP2 = false>
; __device__ __forceinline__ void gemm_phase(PG8_LAS unsigned char* lds, const Gemm g, const Sched& S, const Epi& E, const int tid) {
;     ...
;         for (int t = 0; t < nt; t += 2) {
;     ...
;             PG8_LDA(At, 1, 1); PG8_STAGE(PG8_SB(1, 0), b3, voffB); PG8_STAGE(PG8_SB(1, 1), b3 + hstep, voffB); PG8_STAGE(PG8_SA(1, 0), a3, voffA);
;             PG8_WAIT_V(8); PG8_WAIT_L(0); PG8_BAR; PG8_MMA(1, 0, At, B0); PG8_MMA(1, 1, At, B1); PG8_BAR; PG8_SCHED;
	s_add_i32 s3, s3, s26
	v_lshl_add_u64 v[162:163], v[162:163], 0, s[46:47]
	s_mov_b32 m0, s3
	ds_read_b128 v[176:179], v228 offset:49152
	ds_read_b128 v[180:183], v228 offset:50176
	ds_read_b128 v[186:189], v228 offset:51200
	ds_read_b128 v[190:193], v228 offset:52224
	ds_read_b128 v[194:197], v228 offset:53248
	ds_read_b128 v[198:201], v228 offset:54272
	ds_read_b128 v[202:205], v228 offset:55296
	ds_read_b128 v[206:209], v228 offset:56320
	global_load_lds_dwordx4 v[162:163], off
	s_add_i32 m0, s3, 0x2000
	s_add_u32 s16, s20, 0x160080
	v_lshl_add_u64 v[162:163], v[210:211], 0, s[46:47]
	s_addc_u32 s17, s21, 0
	s_add_i32 s3, s42, s26
	global_load_lds_dwordx4 v[162:163], off
	v_lshl_add_u64 v[162:163], s[16:17], 0, v[2:3]
	s_mov_b32 m0, s3
	s_nop 0
	global_load_lds_dwordx4 v[162:163], off
	v_lshl_add_u64 v[162:163], s[16:17], 0, v[166:167]
	s_add_i32 m0, s3, 0x2000
	s_nop 0
	global_load_lds_dwordx4 v[162:163], off
	v_lshl_add_u64 v[162:163], v[212:213], 0, s[46:47]
	s_mov_b32 m0, s31
	s_nop 0
	global_load_lds_dwordx4 v[162:163], off
	v_lshl_add_u64 v[162:163], v[214:215], 0, s[46:47]
	s_mov_b32 m0, s37
	s_nop 0
	global_load_lds_dwordx4 v[162:163], off
	s_waitcnt vmcnt(8)
	s_waitcnt lgkmcnt(0)
	s_setprio 1
	s_barrier
	v_mfma_f32_16x16x32_bf16 v[64:67], v[134:137], v[176:179], v[64:67]
	v_mfma_f32_16x16x32_bf16 v[60:63], v[142:145], v[176:179], v[60:63]
	v_mfma_f32_16x16x32_bf16 v[48:51], v[134:137], v[186:189], v[48:51]
	v_mfma_f32_16x16x32_bf16 v[44:47], v[142:145], v[186:189], v[44:47]
	v_mfma_f32_16x16x32_bf16 v[32:35], v[134:137], v[194:197], v[32:35]
	v_mfma_f32_16x16x32_bf16 v[28:31], v[142:145], v[194:197], v[28:31]
	v_mfma_f32_16x16x32_bf16 v[16:19], v[134:137], v[202:205], v[16:19]
	v_mfma_f32_16x16x32_bf16 v[12:15], v[142:145], v[202:205], v[12:15]
	v_mfma_f32_16x16x32_bf16 v[64:67], v[138:141], v[180:183], v[64:67]
	v_mfma_f32_16x16x32_bf16 v[60:63], v[146:149], v[180:183], v[60:63]
	v_mfma_f32_16x16x32_bf16 v[48:51], v[138:141], v[190:193], v[48:51]
	v_mfma_f32_16x16x32_bf16 v[44:47], v[146:149], v[190:193], v[44:47]
	v_mfma_f32_16x16x32_bf16 v[32:35], v[138:141], v[198:201], v[32:35]
	v_mfma_f32_16x16x32_bf16 v[28:31], v[146:149], v[198:201], v[28:31]
	v_mfma_f32_16x16x32_bf16 v[16:19], v[138:141], v[206:209], v[16:19]
	v_mfma_f32_16x16x32_bf16 v[12:15], v[146:149], v[206:209], v[12:15]
	s_setprio 0
	s_setprio 1
	v_mfma_f32_16x16x32_bf16 v[56:59], v[150:153], v[176:179], v[56:59]
	v_mfma_f32_16x16x32_bf16 v[52:55], v[158:161], v[176:179], v[52:55]
	v_mfma_f32_16x16x32_bf16 v[40:43], v[150:153], v[186:189], v[40:43]
	v_mfma_f32_16x16x32_bf16 v[36:39], v[158:161], v[186:189], v[36:39]
	v_mfma_f32_16x16x32_bf16 v[24:27], v[150:153], v[194:197], v[24:27]
	v_mfma_f32_16x16x32_bf16 v[20:23], v[158:161], v[194:197], v[20:23]
	v_mfma_f32_16x16x32_bf16 v[8:11], v[150:153], v[202:205], v[8:11]
	v_mfma_f32_16x16x32_bf16 v[4:7], v[158:161], v[202:205], v[4:7]
	v_mfma_f32_16x16x32_bf16 v[56:59], v[154:157], v[180:183], v[56:59]
	v_mfma_f32_16x16x32_bf16 v[52:55], v[172:175], v[180:183], v[52:55]
	v_mfma_f32_16x16x32_bf16 v[40:43], v[154:157], v[190:193], v[40:43]
	v_mfma_f32_16x16x32_bf16 v[36:39], v[172:175], v[190:193], v[36:39]
	v_mfma_f32_16x16x32_bf16 v[24:27], v[154:157], v[198:201], v[24:27]
	v_mfma_f32_16x16x32_bf16 v[20:23], v[172:175], v[198:201], v[20:23]
	v_mfma_f32_16x16x32_bf16 v[8:11], v[154:157], v[206:209], v[8:11]
	v_mfma_f32_16x16x32_bf16 v[4:7], v[172:175], v[206:209], v[4:7]
	s_setprio 0
	s_barrier
	s_add_i32 s75, s75, 2
	s_add_u32 s55, s55, 0x100
	s_addc_u32 s74, s74, 0
	s_cmpk_gt_u32 s75, 0x55
	s_mov_b64 s[16:17], s[18:19]
	s_cbranch_scc1 .LBB0_45

; #define PG8_STAGE(bufoff, gbase, voff) do { _Pragma("unroll") for (int _i = 0; _i < 2; ++_i) \
;         __builtin_amdgcn_global_load_lds((const unsigned*)((const char*)(gbase) + (voff)[_i]), (PG8_LAS unsigned*)(lds + (bufoff) + ldsw + _i * 8192), 16, 0, 0); } while (0)
; #define PG8_LDA(dst, b, h) do { _Pragma("unroll") for (int m = 0; m < 4; ++m) _Pragma("unroll") for (int k = 0; k < 2; ++k) dst[m][k] = *(const PG8_LAS bf16x8*)(lds + PG8_SA(b, h) + aoff + m * 2048 + k * 1024); } while (0)
; #define PG8_LDB(dst, b, h) do { _Pragma("unroll") for (int n = 0; n < 2; ++n) _Pragma("unroll") for (int k = 0; k < 2; ++k) dst[n][k] = *(const PG8_LAS bf16x8*)(lds + PG8_SB(b, h) + boff + n * 2048 + k * 1024); } while (0)
; #define PG8_MMA(ai, bj, At, Bt) do { __builtin_amdgcn_s_setprio(1); _Pragma("unroll") for (int m = 0; m < 4; ++m) _Pragma("unroll") for (int n = 0; n < 2; ++n) _Pragma("unroll") for (int k = 0; k < 2; ++k) \
;         acc[ai][bj][m][n] = __builtin_amdgcn_mfma_f32_16x16x32_bf16(Bt[n][k], At[m][k], acc[ai][bj][m][n], 0, 0, 0); __builtin_amdgcn_s_setprio(0); } while (0)
; #define PG8_WAIT_V(n) asm volatile("s_waitcnt vmcnt(" #n ")" ::: "memory")
; #define PG8_WAIT_L(n) asm volatile("s_waitcnt lgkmcnt(" #n ")" ::: "memory")
; template <class Epi, class Sched, bool ALIGN_EPI = false, bool SP2 = false>
; __device__ __forceinline__ void gemm_phase(PG8_LAS unsigned char* lds, const Gemm g, const Sched& S, const Epi& E, const int tid) {
;     ...
;             const char* a2 = last ? nA : cA + (size_t)(t + 2) * kstep; const char* b2 = last ? nB : cB + (size_t)(t + 2) * kstep;
;             const char* a3 = a2 + kstep; const char* b3 = b2 + kstep;
;             if (last && has_next) S.a_ready(nxt);
;             if (last) E.prefetch(lds + EPI_LDS_OFF + wid * 1024, cur, wr, wc, lane);
;             if constexpr (SP2) {
;             PG8_LDB(B0, 0, 0); PG8_LDB(B1, 0, 1); PG8_SCHED; PG8_LDA(At, 0, 0); PG8_STAGE(PG8_SA(1, 1), a1 + hstep, voffA);
;             PG8_WAIT_V(8); PG8_WAIT_L(0); PG8_BAR; PG8_MMA(0, 0, At, B0); PG8_MMA(0, 1, At, B1); PG8_BAR; PG8_SCHED;
;             PG8_LDA(At, 0, 1); PG8_STAGE(PG8_SB(0, 0), b2, voffB); PG8_STAGE(PG8_SB(0, 1), b2 + hstep, voffB); PG8_STAGE(PG8_SA(0, 0), a2, voffA);
;             PG8_WAIT_V(8); PG8_WAIT_L(0); PG8_BAR; PG8_MMA(1, 0, At, B0); PG8_MMA(1, 1, At, B1); PG8_BAR; PG8_SCHED;
.LBB0_74:
	s_add_u32 s30, s24, 0xfff80080
	s_addc_u32 s31, s25, -1
	s_and_b64 s[28:29], s[28:29], exec
	s_cselect_b32 s31, s17, s31
	s_cselect_b32 s30, s23, s30
	s_cselect_b32 s29, s99, s50
	s_cselect_b32 s28, vcc_lo, vcc_hi
	s_add_i32 s42, 0, 0x10000
	v_add_u32_e32 v110, s42, v247
	s_add_i32 s3, 0, 0x14000
	ds_read_b128 v[98:101], v110
	ds_read_b128 v[102:105], v110 offset:1024
	ds_read_b128 v[106:109], v110 offset:2048
	ds_read_b128 v[144:147], v110 offset:3072
	v_add_u32_e32 v110, s3, v247
	ds_read_b128 v[152:155], v110
	ds_read_b128 v[156:159], v110 offset:1024
	ds_read_b128 v[160:163], v110 offset:2048
	ds_read_b128 v[164:167], v110 offset:3072
	v_lshl_add_u64 v[110:111], s[24:25], 0, v[190:191]
	s_add_i32 m0, s49, 0xc000
	ds_read_b128 v[168:171], v253
	ds_read_b128 v[172:175], v253 offset:1024
	ds_read_b128 v[176:179], v253 offset:2048
	ds_read_b128 v[194:197], v253 offset:3072
	ds_read_b128 v[198:201], v253 offset:4096
	ds_read_b128 v[202:205], v253 offset:5120
	ds_read_b128 v[206:209], v253 offset:6144
	ds_read_b128 v[210:213], v253 offset:7168
	global_load_lds_dwordx4 v[110:111], off
	v_lshl_add_u64 v[110:111], s[24:25], 0, v[192:193]
	s_add_i32 m0, s49, 0xe000
	s_nop 0
	global_load_lds_dwordx4 v[110:111], off
	s_waitcnt vmcnt(8)
	s_waitcnt lgkmcnt(0)
	s_setprio 1
	s_barrier
	v_mfma_f32_16x16x32_bf16 v[148:151], v[98:101], v[168:171], v[148:151]
	v_mfma_f32_16x16x32_bf16 v[140:143], v[106:109], v[168:171], v[140:143]
	v_mfma_f32_16x16x32_bf16 v[128:131], v[98:101], v[176:179], v[128:131]
	v_mfma_f32_16x16x32_bf16 v[124:127], v[106:109], v[176:179], v[124:127]
	v_mfma_f32_16x16x32_bf16 v[110:113], v[98:101], v[198:201], v[112:115]
	v_mfma_f32_16x16x32_bf16 v[92:95], v[106:109], v[198:201], v[92:95]
	v_mfma_f32_16x16x32_bf16 v[80:83], v[98:101], v[206:209], v[80:83]
	v_mfma_f32_16x16x32_bf16 v[76:79], v[106:109], v[206:209], v[76:79]
	v_mfma_f32_16x16x32_bf16 v[148:151], v[102:105], v[172:175], v[148:151]
	v_mfma_f32_16x16x32_bf16 v[140:143], v[144:147], v[172:175], v[140:143]
	v_mfma_f32_16x16x32_bf16 v[128:131], v[102:105], v[194:197], v[128:131]
	v_mfma_f32_16x16x32_bf16 v[124:127], v[144:147], v[194:197], v[124:127]
	v_mfma_f32_16x16x32_bf16 v[110:113], v[102:105], v[202:205], v[110:113]
	v_mfma_f32_16x16x32_bf16 v[92:95], v[144:147], v[202:205], v[92:95]
	v_mfma_f32_16x16x32_bf16 v[80:83], v[102:105], v[210:213], v[80:83]
	v_mfma_f32_16x16x32_bf16 v[76:79], v[144:147], v[210:213], v[76:79]
	s_setprio 0
	s_setprio 1
	v_mfma_f32_16x16x32_bf16 v[136:139], v[152:155], v[168:171], v[136:139]
	v_mfma_f32_16x16x32_bf16 v[132:135], v[160:163], v[168:171], v[132:135]
	v_mfma_f32_16x16x32_bf16 v[120:123], v[152:155], v[176:179], v[120:123]
	v_mfma_f32_16x16x32_bf16 v[114:117], v[160:163], v[176:179], v[116:119]
	v_mfma_f32_16x16x32_bf16 v[88:91], v[152:155], v[198:201], v[88:91]
	v_mfma_f32_16x16x32_bf16 v[84:87], v[160:163], v[198:201], v[84:87]
	v_mfma_f32_16x16x32_bf16 v[72:75], v[152:155], v[206:209], v[72:75]
	v_mfma_f32_16x16x32_bf16 v[68:71], v[160:163], v[206:209], v[68:71]
	v_mfma_f32_16x16x32_bf16 v[136:139], v[156:159], v[172:175], v[136:139]
	v_mfma_f32_16x16x32_bf16 v[132:135], v[164:167], v[172:175], v[132:135]
	v_mfma_f32_16x16x32_bf16 v[120:123], v[156:159], v[194:197], v[120:123]
	v_mfma_f32_16x16x32_bf16 v[116:119], v[164:167], v[194:197], v[114:117]
	v_mfma_f32_16x16x32_bf16 v[88:91], v[156:159], v[202:205], v[88:91]
	v_mfma_f32_16x16x32_bf16 v[84:87], v[164:167], v[202:205], v[84:87]
	v_mfma_f32_16x16x32_bf16 v[72:75], v[156:159], v[210:213], v[72:75]
	v_mfma_f32_16x16x32_bf16 v[68:71], v[164:167], v[210:213], v[68:71]
	s_setprio 0
	s_barrier
	s_add_i32 s42, s42, s48
	v_lshl_add_u64 v[180:181], s[28:29], 0, v[2:3]
	s_mov_b32 m0, s42
	ds_read_b128 v[168:171], v253 offset:16384
	ds_read_b128 v[172:175], v253 offset:17408
	ds_read_b128 v[176:179], v253 offset:18432
	ds_read_b128 v[194:197], v253 offset:19456
	ds_read_b128 v[198:201], v253 offset:20480
	ds_read_b128 v[202:205], v253 offset:21504
	ds_read_b128 v[206:209], v253 offset:22528
	ds_read_b128 v[210:213], v253 offset:23552
	global_load_lds_dwordx4 v[180:181], off
	s_add_i32 m0, s42, 0x2000
	s_add_u32 s42, s28, 0x80000
	v_lshl_add_u64 v[182:183], s[28:29], 0, v[188:189]
	s_addc_u32 s43, s29, 0
	s_add_i32 s3, s3, s48
	global_load_lds_dwordx4 v[182:183], off
	v_lshl_add_u64 v[114:115], s[42:43], 0, v[2:3]
	s_mov_b32 m0, s3
	v_lshl_add_u64 v[214:215], s[30:31], 0, v[0:1]
	global_load_lds_dwordx4 v[114:115], off
	v_lshl_add_u64 v[114:115], s[42:43], 0, v[188:189]
	s_add_i32 m0, s3, 0x2000
	v_lshl_add_u64 v[216:217], s[30:31], 0, v[186:187]
	global_load_lds_dwordx4 v[114:115], off
	s_mov_b32 m0, s49
	s_nop 0
	global_load_lds_dwordx4 v[214:215], off
	s_mov_b32 m0, s52
	s_nop 0
	global_load_lds_dwordx4 v[216:217], off
	s_waitcnt vmcnt(8)
	s_waitcnt lgkmcnt(0)
	s_setprio 1
	s_barrier
; #define PG8_STAGE(bufoff, gbase, voff) do { _Pragma("unroll") for (int _i = 0; _i < 2; ++_i) \
;         __builtin_amdgcn_global_load_lds((const unsigned*)((const char*)(gbase) + (voff)[_i]), (PG8_LAS unsigned*)(lds + (bufoff) + ldsw + _i * 8192), 16, 0, 0); } while (0)
; #define PG8_LDA(dst, b, h) do { _Pragma("unroll") for (int m = 0; m < 4; ++m) _Pragma("unroll") for (int k = 0; k < 2; ++k) dst[m][k] = *(const PG8_LAS bf16x8*)(lds + PG8_SA(b, h) + aoff + m * 2048 + k * 1024); } while (0)
; #define PG8_LDB(dst, b, h) do { _Pragma("unroll") for (int n = 0; n < 2; ++n) _Pragma("unroll") for (int k = 0; k < 2; ++k) dst[n][k] = *(const PG8_LAS bf16x8*)(lds + PG8_SB(b, h) + boff + n * 2048 + k * 1024); } while (0)
; #define PG8_MMA(ai, bj, At, Bt) do { __builtin_amdgcn_s_setprio(1); _Pragma("unroll") for (int m = 0; m < 4; ++m) _Pragma("unroll") for (int n = 0; n < 2; ++n) _Pragma("unroll") for (int k = 0; k < 2; ++k) \
;         acc[ai][bj][m][n] = __builtin_amdgcn_mfma_f32_16x16x32_bf16(Bt[n][k], At[m][k], acc[ai][bj][m][n], 0, 0, 0); __builtin_amdgcn_s_setprio(0); } while (0)
; #define PG8_WAIT_V(n) asm volatile("s_waitcnt vmcnt(" #n ")" ::: "memory")
; #define PG8_WAIT_L(n) asm volatile("s_waitcnt lgkmcnt(" #n ")" ::: "memory")
; #define PG8_BAR __builtin_amdgcn_s_barrier()
; #define PG8_SCHED __builtin_amdgcn_sched_barrier(0)
; template <class Epi, class Sched, bool ALIGN_EPI = false, bool SP2 = false>
; __device__ __forceinline__ void gemm_phase(PG8_LAS unsigned char* lds, const Gemm g, const Sched& S, const Epi& E, const int tid) {
;     ...
;             PG8_WAIT_V(8); PG8_WAIT_L(0); PG8_BAR; PG8_MMA(1, 0, At, B0); PG8_MMA(1, 1, At, B1); PG8_BAR; PG8_SCHED;
;             PG8_LDB(B0, 1, 0); PG8_LDB(B1, 1, 1); PG8_SCHED; PG8_LDA(At, 1, 0); PG8_STAGE(PG8_SA(0, 1), a2 + hstep, voffA);
;             PG8_WAIT_V(8); PG8_WAIT_L(0); PG8_BAR; PG8_MMA(0, 0, At, B0); PG8_MMA(0, 1, At, B1); PG8_BAR; PG8_SCHED;
	v_mfma_f32_16x16x32_bf16 v[64:67], v[98:101], v[168:171], v[64:67]
	v_mfma_f32_16x16x32_bf16 v[60:63], v[106:109], v[168:171], v[60:63]
	v_mfma_f32_16x16x32_bf16 v[48:51], v[98:101], v[176:179], v[48:51]
	v_mfma_f32_16x16x32_bf16 v[44:47], v[106:109], v[176:179], v[44:47]
	v_mfma_f32_16x16x32_bf16 v[32:35], v[98:101], v[198:201], v[32:35]
	v_mfma_f32_16x16x32_bf16 v[28:31], v[106:109], v[198:201], v[28:31]
	v_mfma_f32_16x16x32_bf16 v[16:19], v[98:101], v[206:209], v[16:19]
	v_mfma_f32_16x16x32_bf16 v[12:15], v[106:109], v[206:209], v[12:15]
	v_mfma_f32_16x16x32_bf16 v[64:67], v[102:105], v[172:175], v[64:67]
	v_mfma_f32_16x16x32_bf16 v[60:63], v[144:147], v[172:175], v[60:63]
	v_mfma_f32_16x16x32_bf16 v[48:51], v[102:105], v[194:197], v[48:51]
	v_mfma_f32_16x16x32_bf16 v[44:47], v[144:147], v[194:197], v[44:47]
	v_mfma_f32_16x16x32_bf16 v[32:35], v[102:105], v[202:205], v[32:35]
	v_mfma_f32_16x16x32_bf16 v[28:31], v[144:147], v[202:205], v[28:31]
	v_mfma_f32_16x16x32_bf16 v[16:19], v[102:105], v[210:213], v[16:19]
	v_mfma_f32_16x16x32_bf16 v[12:15], v[144:147], v[210:213], v[12:15]
	s_setprio 0
	s_setprio 1
	v_mfma_f32_16x16x32_bf16 v[56:59], v[152:155], v[168:171], v[56:59]
	v_mfma_f32_16x16x32_bf16 v[52:55], v[160:163], v[168:171], v[52:55]
	v_mfma_f32_16x16x32_bf16 v[40:43], v[152:155], v[176:179], v[40:43]
	v_mfma_f32_16x16x32_bf16 v[36:39], v[160:163], v[176:179], v[36:39]
	v_mfma_f32_16x16x32_bf16 v[24:27], v[152:155], v[198:201], v[24:27]
	v_mfma_f32_16x16x32_bf16 v[20:23], v[160:163], v[198:201], v[20:23]
	v_mfma_f32_16x16x32_bf16 v[8:11], v[152:155], v[206:209], v[8:11]
	v_mfma_f32_16x16x32_bf16 v[4:7], v[160:163], v[206:209], v[4:7]
	v_mfma_f32_16x16x32_bf16 v[56:59], v[156:159], v[172:175], v[56:59]
	v_mfma_f32_16x16x32_bf16 v[52:55], v[164:167], v[172:175], v[52:55]
	v_mfma_f32_16x16x32_bf16 v[40:43], v[156:159], v[194:197], v[40:43]
	v_mfma_f32_16x16x32_bf16 v[36:39], v[164:167], v[194:197], v[36:39]
	v_mfma_f32_16x16x32_bf16 v[24:27], v[156:159], v[202:205], v[24:27]
	v_mfma_f32_16x16x32_bf16 v[20:23], v[164:167], v[202:205], v[20:23]
	v_mfma_f32_16x16x32_bf16 v[8:11], v[156:159], v[210:213], v[8:11]
	v_mfma_f32_16x16x32_bf16 v[4:7], v[164:167], v[210:213], v[4:7]
	s_setprio 0
	s_barrier
	s_add_i32 s3, 0, 0x18000
	v_add_u32_e32 v114, s3, v247
	s_add_i32 s42, 0, 0x1c000
	ds_read_b128 v[98:101], v114
	ds_read_b128 v[102:105], v114 offset:1024
	ds_read_b128 v[106:109], v114 offset:2048
	ds_read_b128 v[144:147], v114 offset:3072
	v_add_u32_e32 v114, s42, v247
	ds_read_b128 v[152:155], v114
	ds_read_b128 v[156:159], v114 offset:1024
	ds_read_b128 v[160:163], v114 offset:2048
	ds_read_b128 v[164:167], v114 offset:3072
	s_add_u32 s30, s30, 0x80000
	s_addc_u32 s31, s31, 0
	s_mov_b32 m0, s53
	v_lshl_add_u64 v[114:115], s[30:31], 0, v[0:1]
	ds_read_b128 v[168:171], v253 offset:32768
	ds_read_b128 v[172:175], v253 offset:33792
	ds_read_b128 v[176:179], v253 offset:34816
	ds_read_b128 v[194:197], v253 offset:35840
	ds_read_b128 v[198:201], v253 offset:36864
	ds_read_b128 v[202:205], v253 offset:37888
	ds_read_b128 v[206:209], v253 offset:38912
	ds_read_b128 v[210:213], v253 offset:39936
	global_load_lds_dwordx4 v[114:115], off
	v_lshl_add_u64 v[114:115], s[30:31], 0, v[186:187]
	s_mov_b32 m0, s54
	s_nop 0
	global_load_lds_dwordx4 v[114:115], off
	s_waitcnt vmcnt(8)
	s_waitcnt lgkmcnt(0)
	s_setprio 1
	s_barrier
	v_mfma_f32_16x16x32_bf16 v[148:151], v[98:101], v[168:171], v[148:151]
	v_mfma_f32_16x16x32_bf16 v[140:143], v[106:109], v[168:171], v[140:143]
	v_mfma_f32_16x16x32_bf16 v[128:131], v[98:101], v[176:179], v[128:131]
	v_mfma_f32_16x16x32_bf16 v[124:127], v[106:109], v[176:179], v[124:127]
	v_mfma_f32_16x16x32_bf16 v[110:113], v[98:101], v[198:201], v[110:113]
	v_mfma_f32_16x16x32_bf16 v[92:95], v[106:109], v[198:201], v[92:95]
	v_mfma_f32_16x16x32_bf16 v[80:83], v[98:101], v[206:209], v[80:83]
	v_mfma_f32_16x16x32_bf16 v[76:79], v[106:109], v[206:209], v[76:79]
	v_mfma_f32_16x16x32_bf16 v[148:151], v[102:105], v[172:175], v[148:151]
	v_mfma_f32_16x16x32_bf16 v[140:143], v[144:147], v[172:175], v[140:143]
	v_mfma_f32_16x16x32_bf16 v[128:131], v[102:105], v[194:197], v[128:131]
	v_mfma_f32_16x16x32_bf16 v[124:127], v[144:147], v[194:197], v[124:127]
	v_mfma_f32_16x16x32_bf16 v[112:115], v[102:105], v[202:205], v[110:113]
	v_mfma_f32_16x16x32_bf16 v[92:95], v[144:147], v[202:205], v[92:95]
	v_mfma_f32_16x16x32_bf16 v[80:83], v[102:105], v[210:213], v[80:83]
	v_mfma_f32_16x16x32_bf16 v[76:79], v[144:147], v[210:213], v[76:79]
	s_setprio 0
	s_setprio 1
	v_mfma_f32_16x16x32_bf16 v[136:139], v[152:155], v[168:171], v[136:139]
	v_mfma_f32_16x16x32_bf16 v[132:135], v[160:163], v[168:171], v[132:135]
	v_mfma_f32_16x16x32_bf16 v[120:123], v[152:155], v[176:179], v[120:123]
	v_mfma_f32_16x16x32_bf16 v[116:119], v[160:163], v[176:179], v[116:119]
	v_mfma_f32_16x16x32_bf16 v[88:91], v[152:155], v[198:201], v[88:91]
	v_mfma_f32_16x16x32_bf16 v[84:87], v[160:163], v[198:201], v[84:87]
	v_mfma_f32_16x16x32_bf16 v[72:75], v[152:155], v[206:209], v[72:75]
	v_mfma_f32_16x16x32_bf16 v[68:71], v[160:163], v[206:209], v[68:71]
	v_mfma_f32_16x16x32_bf16 v[136:139], v[156:159], v[172:175], v[136:139]
	v_mfma_f32_16x16x32_bf16 v[132:135], v[164:167], v[172:175], v[132:135]
	v_mfma_f32_16x16x32_bf16 v[120:123], v[156:159], v[194:197], v[120:123]
	v_mfma_f32_16x16x32_bf16 v[116:119], v[164:167], v[194:197], v[116:119]
	v_mfma_f32_16x16x32_bf16 v[88:91], v[156:159], v[202:205], v[88:91]
	v_mfma_f32_16x16x32_bf16 v[84:87], v[164:167], v[202:205], v[84:87]
	v_mfma_f32_16x16x32_bf16 v[72:75], v[156:159], v[210:213], v[72:75]
	v_mfma_f32_16x16x32_bf16 v[68:71], v[164:167], v[210:213], v[68:71]
	s_setprio 0
	s_barrier
; #define PG8_STAGE(bufoff, gbase, voff) do { _Pragma("unroll") for (int _i = 0; _i < 2; ++_i) \
;         __builtin_amdgcn_global_load_lds((const unsigned*)((const char*)(gbase) + (voff)[_i]), (PG8_LAS unsigned*)(lds + (bufoff) + ldsw + _i * 8192), 16, 0, 0); } while (0)
; #define PG8_LDA(dst, b, h) do { _Pragma("unroll") for (int m = 0; m < 4; ++m) _Pragma("unroll") for (int k = 0; k < 2; ++k) dst[m][k] = *(const PG8_LAS bf16x8*)(lds + PG8_SA(b, h) + aoff + m * 2048 + k * 1024); } while (0)
; #define PG8_MMA(ai, bj, At, Bt) do { __builtin_amdgcn_s_setprio(1); _Pragma("unroll") for (int m = 0; m < 4; ++m) _Pragma("unroll") for (int n = 0; n < 2; ++n) _Pragma("unroll") for (int k = 0; k < 2; ++k) \
;         acc[ai][bj][m][n] = __builtin_amdgcn_mfma_f32_16x16x32_bf16(Bt[n][k], At[m][k], acc[ai][bj][m][n], 0, 0, 0); __builtin_amdgcn_s_setprio(0); } while (0)
; #define PG8_WAIT_V(n) asm volatile("s_waitcnt vmcnt(" #n ")" ::: "memory")
; #define PG8_WAIT_L(n) asm volatile("s_waitcnt lgkmcnt(" #n ")" ::: "memory")
; #define PG8_BAR __builtin_amdgcn_s_barrier()
; #define PG8_SCHED __builtin_amdgcn_sched_barrier(0)
; template <class Epi, class Sched, bool ALIGN_EPI = false, bool SP2 = false>
; __device__ __forceinline__ void gemm_phase(PG8_LAS unsigned char* lds, const Gemm g, const Sched& S, const Epi& E, const int tid) {
;     ...
;         for (int t = 0; t < nt; t += 2) {
;     ...
;             PG8_LDA(At, 1, 1); PG8_STAGE(PG8_SB(1, 0), b3, voffB); PG8_STAGE(PG8_SB(1, 1), b3 + hstep, voffB); PG8_STAGE(PG8_SA(1, 0), a3, voffA);
;             PG8_WAIT_V(8); PG8_WAIT_L(0); PG8_BAR; PG8_MMA(1, 0, At, B0); PG8_MMA(1, 1, At, B1); PG8_BAR; PG8_SCHED;
	s_add_i32 s3, s3, s48
	v_lshl_add_u64 v[110:111], v[180:181], 0, s[46:47]
	s_mov_b32 m0, s3
	ds_read_b128 v[168:171], v253 offset:49152
	ds_read_b128 v[172:175], v253 offset:50176
	ds_read_b128 v[176:179], v253 offset:51200
	ds_read_b128 v[194:197], v253 offset:52224
	ds_read_b128 v[198:201], v253 offset:53248
	ds_read_b128 v[202:205], v253 offset:54272
	ds_read_b128 v[206:209], v253 offset:55296
	ds_read_b128 v[210:213], v253 offset:56320
	global_load_lds_dwordx4 v[110:111], off
	s_add_i32 m0, s3, 0x2000
	s_add_u32 s28, s28, 0x80080
	v_lshl_add_u64 v[110:111], v[182:183], 0, s[46:47]
	s_addc_u32 s29, s29, 0
	s_add_i32 s3, s42, s48
	global_load_lds_dwordx4 v[110:111], off
	v_lshl_add_u64 v[110:111], s[28:29], 0, v[2:3]
	s_mov_b32 m0, s3
	s_nop 0
	global_load_lds_dwordx4 v[110:111], off
	v_lshl_add_u64 v[110:111], s[28:29], 0, v[188:189]
	s_add_i32 m0, s3, 0x2000
	s_nop 0
	global_load_lds_dwordx4 v[110:111], off
	v_lshl_add_u64 v[110:111], v[214:215], 0, s[46:47]
	s_mov_b32 m0, s55
	s_nop 0
	global_load_lds_dwordx4 v[110:111], off
	v_lshl_add_u64 v[110:111], v[216:217], 0, s[46:47]
	s_mov_b32 m0, s74
	s_nop 0
	global_load_lds_dwordx4 v[110:111], off
	s_waitcnt vmcnt(8)
	s_waitcnt lgkmcnt(0)
	s_setprio 1
	s_barrier
	v_mfma_f32_16x16x32_bf16 v[64:67], v[98:101], v[168:171], v[64:67]
	v_mfma_f32_16x16x32_bf16 v[60:63], v[106:109], v[168:171], v[60:63]
	v_mfma_f32_16x16x32_bf16 v[48:51], v[98:101], v[176:179], v[48:51]
	v_mfma_f32_16x16x32_bf16 v[44:47], v[106:109], v[176:179], v[44:47]
	v_mfma_f32_16x16x32_bf16 v[32:35], v[98:101], v[198:201], v[32:35]
	v_mfma_f32_16x16x32_bf16 v[28:31], v[106:109], v[198:201], v[28:31]
	v_mfma_f32_16x16x32_bf16 v[16:19], v[98:101], v[206:209], v[16:19]
	v_mfma_f32_16x16x32_bf16 v[12:15], v[106:109], v[206:209], v[12:15]
	v_mfma_f32_16x16x32_bf16 v[64:67], v[102:105], v[172:175], v[64:67]
	v_mfma_f32_16x16x32_bf16 v[60:63], v[144:147], v[172:175], v[60:63]
	v_mfma_f32_16x16x32_bf16 v[48:51], v[102:105], v[194:197], v[48:51]
	v_mfma_f32_16x16x32_bf16 v[44:47], v[144:147], v[194:197], v[44:47]
	v_mfma_f32_16x16x32_bf16 v[32:35], v[102:105], v[202:205], v[32:35]
	v_mfma_f32_16x16x32_bf16 v[28:31], v[144:147], v[202:205], v[28:31]
	v_mfma_f32_16x16x32_bf16 v[16:19], v[102:105], v[210:213], v[16:19]
	v_mfma_f32_16x16x32_bf16 v[12:15], v[144:147], v[210:213], v[12:15]
	s_setprio 0
	s_setprio 1
	v_mfma_f32_16x16x32_bf16 v[56:59], v[152:155], v[168:171], v[56:59]
	v_mfma_f32_16x16x32_bf16 v[52:55], v[160:163], v[168:171], v[52:55]
	v_mfma_f32_16x16x32_bf16 v[40:43], v[152:155], v[176:179], v[40:43]
	v_mfma_f32_16x16x32_bf16 v[36:39], v[160:163], v[176:179], v[36:39]
	v_mfma_f32_16x16x32_bf16 v[24:27], v[152:155], v[198:201], v[24:27]
	v_mfma_f32_16x16x32_bf16 v[20:23], v[160:163], v[198:201], v[20:23]
	v_mfma_f32_16x16x32_bf16 v[8:11], v[152:155], v[206:209], v[8:11]
	v_mfma_f32_16x16x32_bf16 v[4:7], v[160:163], v[206:209], v[4:7]
	v_mfma_f32_16x16x32_bf16 v[56:59], v[156:159], v[172:175], v[56:59]
	v_mfma_f32_16x16x32_bf16 v[52:55], v[164:167], v[172:175], v[52:55]
	v_mfma_f32_16x16x32_bf16 v[40:43], v[156:159], v[194:197], v[40:43]
	v_mfma_f32_16x16x32_bf16 v[36:39], v[164:167], v[194:197], v[36:39]
	v_mfma_f32_16x16x32_bf16 v[24:27], v[156:159], v[202:205], v[24:27]
	v_mfma_f32_16x16x32_bf16 v[20:23], v[164:167], v[202:205], v[20:23]
	v_mfma_f32_16x16x32_bf16 v[8:11], v[156:159], v[210:213], v[8:11]
	v_mfma_f32_16x16x32_bf16 v[4:7], v[164:167], v[210:213], v[4:7]
	s_setprio 0
	s_barrier
	s_add_i32 s51, s51, 2
	s_add_u32 s24, s24, 0x100
	s_addc_u32 s25, s25, 0
	s_add_u32 vcc_hi, vcc_hi, 0x100
	s_addc_u32 s50, s50, 0
	s_cmp_gt_u32 s51, 29
	s_cbranch_scc1 .LBB0_77

; #define PG8_STAGE(bufoff, gbase, voff) do { _Pragma("unroll") for (int _i = 0; _i < 2; ++_i) \
;         __builtin_amdgcn_global_load_lds((const unsigned*)((const char*)(gbase) + (voff)[_i]), (PG8_LAS unsigned*)(lds + (bufoff) + ldsw + _i * 8192), 16, 0, 0); } while (0)
; #define PG8_LDA(dst, b, h) do { _Pragma("unroll") for (int m = 0; m < 4; ++m) _Pragma("unroll") for (int k = 0; k < 2; ++k) dst[m][k] = *(const PG8_LAS bf16x8*)(lds + PG8_SA(b, h) + aoff + m * 2048 + k * 1024); } while (0)
; #define PG8_LDB(dst, b, h) do { _Pragma("unroll") for (int n = 0; n < 2; ++n) _Pragma("unroll") for (int k = 0; k < 2; ++k) dst[n][k] = *(const PG8_LAS bf16x8*)(lds + PG8_SB(b, h) + boff + n * 2048 + k * 1024); } while (0)
; #define PG8_MMA(ai, bj, At, Bt) do { __builtin_amdgcn_s_setprio(1); _Pragma("unroll") for (int m = 0; m < 4; ++m) _Pragma("unroll") for (int n = 0; n < 2; ++n) _Pragma("unroll") for (int k = 0; k < 2; ++k) \
;         acc[ai][bj][m][n] = __builtin_amdgcn_mfma_f32_16x16x32_bf16(Bt[n][k], At[m][k], acc[ai][bj][m][n], 0, 0, 0); __builtin_amdgcn_s_setprio(0); } while (0)
; #define PG8_WAIT_V(n) asm volatile("s_waitcnt vmcnt(" #n ")" ::: "memory")
; #define PG8_WAIT_L(n) asm volatile("s_waitcnt lgkmcnt(" #n ")" ::: "memory")
; template <class Epi, class Sched, bool ALIGN_EPI = false, bool SP2 = false>
; __device__ __forceinline__ void gemm_phase(PG8_LAS unsigned char* lds, const Gemm g, const Sched& S, const Epi& E, const int tid) {
;     ...
;             const char* a2 = last ? nA : cA + (size_t)(t + 2) * kstep; const char* b2 = last ? nB : cB + (size_t)(t + 2) * kstep;
;             const char* a3 = a2 + kstep; const char* b3 = b2 + kstep;
;             if (last && has_next) S.a_ready(nxt);
;             if (last) E.prefetch(lds + EPI_LDS_OFF + wid * 1024, cur, wr, wc, lane);
;             if constexpr (SP2) {
;             PG8_LDB(B0, 0, 0); PG8_LDB(B1, 0, 1); PG8_SCHED; PG8_LDA(At, 0, 0); PG8_STAGE(PG8_SA(1, 1), a1 + hstep, voffA);
;             PG8_WAIT_V(8); PG8_WAIT_L(0); PG8_BAR; PG8_MMA(0, 0, At, B0); PG8_MMA(0, 1, At, B1); PG8_BAR; PG8_SCHED;
;             PG8_LDA(At, 0, 1); PG8_STAGE(PG8_SB(0, 0), b2, voffB); PG8_STAGE(PG8_SB(0, 1), b2 + hstep, voffB); PG8_STAGE(PG8_SA(0, 0), a2, voffA);
;             PG8_WAIT_V(8); PG8_WAIT_L(0); PG8_BAR; PG8_MMA(1, 0, At, B0); PG8_MMA(1, 1, At, B1); PG8_BAR; PG8_SCHED;
.LBB0_156:
	s_add_u32 s3, s26, 0xfff80080
	s_addc_u32 s30, s27, -1
	s_and_b64 s[28:29], s[28:29], exec
	s_cselect_b32 s31, s9, s30
	s_cselect_b32 s30, s17, s3
	s_cselect_b32 s29, s15, s25
	s_cselect_b32 s28, s39, s23
	s_add_i32 s3, 0, 0x10000
	v_add_u32_e32 v34, s3, v167
	s_add_i32 s51, 0, 0x14000
	ds_read_b128 v[44:47], v34
	ds_read_b128 v[48:51], v34 offset:1024
	ds_read_b128 v[160:163], v34 offset:2048
	ds_read_b128 v[172:175], v34 offset:3072
	v_add_u32_e32 v34, s51, v167
	ds_read_b128 v[176:179], v34
	ds_read_b128 v[180:183], v34 offset:1024
	ds_read_b128 v[186:189], v34 offset:2048
	ds_read_b128 v[190:193], v34 offset:3072
	v_lshl_add_u64 v[34:35], s[26:27], 0, v[156:157]
	s_add_i32 m0, s48, 0xc000
	ds_read_b128 v[194:197], v171
	ds_read_b128 v[198:201], v171 offset:1024
	ds_read_b128 v[202:205], v171 offset:2048
	ds_read_b128 v[206:209], v171 offset:3072
	ds_read_b128 v[210:213], v171 offset:4096
	ds_read_b128 v[214:217], v171 offset:5120
	ds_read_b128 v[218:221], v171 offset:6144
	ds_read_b128 v[222:225], v171 offset:7168
	global_load_lds_dwordx4 v[34:35], off
	v_lshl_add_u64 v[34:35], s[26:27], 0, v[158:159]
	s_add_i32 m0, s48, 0xe000
	s_nop 0
	global_load_lds_dwordx4 v[34:35], off
	s_waitcnt vmcnt(8)
	s_waitcnt lgkmcnt(0)
	s_setprio 1
	s_barrier
	v_mfma_f32_16x16x32_bf16 v[144:147], v[44:47], v[194:197], v[144:147]
	v_mfma_f32_16x16x32_bf16 v[140:143], v[160:163], v[194:197], v[140:143]
	v_mfma_f32_16x16x32_bf16 v[128:131], v[44:47], v[202:205], v[128:131]
	v_mfma_f32_16x16x32_bf16 v[124:127], v[160:163], v[202:205], v[124:127]
	v_mfma_f32_16x16x32_bf16 v[112:115], v[44:47], v[210:213], v[112:115]
	v_mfma_f32_16x16x32_bf16 v[108:111], v[160:163], v[210:213], v[108:111]
	v_mfma_f32_16x16x32_bf16 v[96:99], v[44:47], v[218:221], v[96:99]
	v_mfma_f32_16x16x32_bf16 v[92:95], v[160:163], v[218:221], v[92:95]
	v_mfma_f32_16x16x32_bf16 v[144:147], v[48:51], v[198:201], v[144:147]
	v_mfma_f32_16x16x32_bf16 v[140:143], v[172:175], v[198:201], v[140:143]
	v_mfma_f32_16x16x32_bf16 v[128:131], v[48:51], v[206:209], v[128:131]
	v_mfma_f32_16x16x32_bf16 v[124:127], v[172:175], v[206:209], v[124:127]
	v_mfma_f32_16x16x32_bf16 v[112:115], v[48:51], v[214:217], v[112:115]
	v_mfma_f32_16x16x32_bf16 v[108:111], v[172:175], v[214:217], v[108:111]
	v_mfma_f32_16x16x32_bf16 v[96:99], v[48:51], v[222:225], v[96:99]
	v_mfma_f32_16x16x32_bf16 v[92:95], v[172:175], v[222:225], v[92:95]
	s_setprio 0
	s_setprio 1
	v_mfma_f32_16x16x32_bf16 v[136:139], v[176:179], v[194:197], v[136:139]
	v_mfma_f32_16x16x32_bf16 v[132:135], v[186:189], v[194:197], v[132:135]
	v_mfma_f32_16x16x32_bf16 v[120:123], v[176:179], v[202:205], v[120:123]
	v_mfma_f32_16x16x32_bf16 v[116:119], v[186:189], v[202:205], v[116:119]
	v_mfma_f32_16x16x32_bf16 v[104:107], v[176:179], v[210:213], v[104:107]
	v_mfma_f32_16x16x32_bf16 v[100:103], v[186:189], v[210:213], v[100:103]
	v_mfma_f32_16x16x32_bf16 v[88:91], v[176:179], v[218:221], v[88:91]
	v_mfma_f32_16x16x32_bf16 v[84:87], v[186:189], v[218:221], v[84:87]
	v_mfma_f32_16x16x32_bf16 v[136:139], v[180:183], v[198:201], v[136:139]
	v_mfma_f32_16x16x32_bf16 v[132:135], v[190:193], v[198:201], v[132:135]
	v_mfma_f32_16x16x32_bf16 v[120:123], v[180:183], v[206:209], v[120:123]
	v_mfma_f32_16x16x32_bf16 v[116:119], v[190:193], v[206:209], v[116:119]
	v_mfma_f32_16x16x32_bf16 v[104:107], v[180:183], v[214:217], v[104:107]
	v_mfma_f32_16x16x32_bf16 v[100:103], v[190:193], v[214:217], v[100:103]
	v_mfma_f32_16x16x32_bf16 v[88:91], v[180:183], v[222:225], v[88:91]
	v_mfma_f32_16x16x32_bf16 v[84:87], v[190:193], v[222:225], v[84:87]
	s_setprio 0
	s_barrier
	s_add_i32 s3, s3, s44
	v_lshl_add_u64 v[164:165], s[28:29], 0, v[2:3]
	s_mov_b32 m0, s3
	ds_read_b128 v[194:197], v171 offset:16384
	ds_read_b128 v[198:201], v171 offset:17408
	ds_read_b128 v[202:205], v171 offset:18432
	ds_read_b128 v[206:209], v171 offset:19456
	ds_read_b128 v[210:213], v171 offset:20480
	ds_read_b128 v[214:217], v171 offset:21504
	ds_read_b128 v[218:221], v171 offset:22528
	ds_read_b128 v[222:225], v171 offset:23552
	global_load_lds_dwordx4 v[164:165], off
	s_add_i32 m0, s3, 0x2000
	s_add_u32 s42, s28, 0x80000
	v_lshl_add_u64 v[226:227], s[28:29], 0, v[150:151]
	s_addc_u32 s43, s29, 0
	s_add_i32 s3, s51, s44
	global_load_lds_dwordx4 v[226:227], off
	v_lshl_add_u64 v[34:35], s[42:43], 0, v[2:3]
	s_mov_b32 m0, s3
	v_lshl_add_u64 v[228:229], s[30:31], 0, v[0:1]
	global_load_lds_dwordx4 v[34:35], off
	v_lshl_add_u64 v[34:35], s[42:43], 0, v[150:151]
	s_add_i32 m0, s3, 0x2000
	v_lshl_add_u64 v[230:231], s[30:31], 0, v[148:149]
	global_load_lds_dwordx4 v[34:35], off
	s_mov_b32 m0, s48
	s_nop 0
	global_load_lds_dwordx4 v[228:229], off
	s_mov_b32 m0, s49
	s_nop 0
	global_load_lds_dwordx4 v[230:231], off
	s_waitcnt vmcnt(8)
	s_waitcnt lgkmcnt(0)
	s_setprio 1
	s_barrier
; #define PG8_STAGE(bufoff, gbase, voff) do { _Pragma("unroll") for (int _i = 0; _i < 2; ++_i) \
;         __builtin_amdgcn_global_load_lds((const unsigned*)((const char*)(gbase) + (voff)[_i]), (PG8_LAS unsigned*)(lds + (bufoff) + ldsw + _i * 8192), 16, 0, 0); } while (0)
; #define PG8_LDA(dst, b, h) do { _Pragma("unroll") for (int m = 0; m < 4; ++m) _Pragma("unroll") for (int k = 0; k < 2; ++k) dst[m][k] = *(const PG8_LAS bf16x8*)(lds + PG8_SA(b, h) + aoff + m * 2048 + k * 1024); } while (0)
; #define PG8_LDB(dst, b, h) do { _Pragma("unroll") for (int n = 0; n < 2; ++n) _Pragma("unroll") for (int k = 0; k < 2; ++k) dst[n][k] = *(const PG8_LAS bf16x8*)(lds + PG8_SB(b, h) + boff + n * 2048 + k * 1024); } while (0)
; #define PG8_MMA(ai, bj, At, Bt) do { __builtin_amdgcn_s_setprio(1); _Pragma("unroll") for (int m = 0; m < 4; ++m) _Pragma("unroll") for (int n = 0; n < 2; ++n) _Pragma("unroll") for (int k = 0; k < 2; ++k) \
;         acc[ai][bj][m][n] = __builtin_amdgcn_mfma_f32_16x16x32_bf16(Bt[n][k], At[m][k], acc[ai][bj][m][n], 0, 0, 0); __builtin_amdgcn_s_setprio(0); } while (0)
; #define PG8_WAIT_V(n) asm volatile("s_waitcnt vmcnt(" #n ")" ::: "memory")
; #define PG8_WAIT_L(n) asm volatile("s_waitcnt lgkmcnt(" #n ")" ::: "memory")
; #define PG8_BAR __builtin_amdgcn_s_barrier()
; #define PG8_SCHED __builtin_amdgcn_sched_barrier(0)
; template <class Epi, class Sched, bool ALIGN_EPI = false, bool SP2 = false>
; __device__ __forceinline__ void gemm_phase(PG8_LAS unsigned char* lds, const Gemm g, const Sched& S, const Epi& E, const int tid) {
;     ...
;             PG8_WAIT_V(8); PG8_WAIT_L(0); PG8_BAR; PG8_MMA(1, 0, At, B0); PG8_MMA(1, 1, At, B1); PG8_BAR; PG8_SCHED;
;             PG8_LDB(B0, 1, 0); PG8_LDB(B1, 1, 1); PG8_SCHED; PG8_LDA(At, 1, 0); PG8_STAGE(PG8_SA(0, 1), a2 + hstep, voffA);
;             PG8_WAIT_V(8); PG8_WAIT_L(0); PG8_BAR; PG8_MMA(0, 0, At, B0); PG8_MMA(0, 1, At, B1); PG8_BAR; PG8_SCHED;
	v_mfma_f32_16x16x32_bf16 v[80:83], v[44:47], v[194:197], v[80:83]
	v_mfma_f32_16x16x32_bf16 v[76:79], v[160:163], v[194:197], v[76:79]
	v_mfma_f32_16x16x32_bf16 v[64:67], v[44:47], v[202:205], v[64:67]
	v_mfma_f32_16x16x32_bf16 v[60:63], v[160:163], v[202:205], v[60:63]
	v_mfma_f32_16x16x32_bf16 v[40:43], v[44:47], v[210:213], v[40:43]
	v_mfma_f32_16x16x32_bf16 v[34:37], v[160:163], v[210:213], v[36:39]
	v_mfma_f32_16x16x32_bf16 v[16:19], v[44:47], v[218:221], v[16:19]
	v_mfma_f32_16x16x32_bf16 v[12:15], v[160:163], v[218:221], v[12:15]
	v_mfma_f32_16x16x32_bf16 v[80:83], v[48:51], v[198:201], v[80:83]
	v_mfma_f32_16x16x32_bf16 v[76:79], v[172:175], v[198:201], v[76:79]
	v_mfma_f32_16x16x32_bf16 v[64:67], v[48:51], v[206:209], v[64:67]
	v_mfma_f32_16x16x32_bf16 v[60:63], v[172:175], v[206:209], v[60:63]
	v_mfma_f32_16x16x32_bf16 v[40:43], v[48:51], v[214:217], v[40:43]
	v_mfma_f32_16x16x32_bf16 v[34:37], v[172:175], v[214:217], v[34:37]
	v_mfma_f32_16x16x32_bf16 v[16:19], v[48:51], v[222:225], v[16:19]
	v_mfma_f32_16x16x32_bf16 v[12:15], v[172:175], v[222:225], v[12:15]
	s_setprio 0
	s_setprio 1
	v_mfma_f32_16x16x32_bf16 v[56:59], v[176:179], v[202:205], v[56:59]
	v_mfma_f32_16x16x32_bf16 v[52:55], v[186:189], v[202:205], v[52:55]
	v_mfma_f32_16x16x32_bf16 v[24:27], v[176:179], v[210:213], v[24:27]
	v_mfma_f32_16x16x32_bf16 v[20:23], v[186:189], v[210:213], v[20:23]
	v_mfma_f32_16x16x32_bf16 v[8:11], v[176:179], v[218:221], v[8:11]
	v_mfma_f32_16x16x32_bf16 v[4:7], v[186:189], v[218:221], v[4:7]
	v_mfma_f32_16x16x32_bf16 v[44:47], v[176:179], v[194:197], v[72:75]
	v_mfma_f32_16x16x32_bf16 v[48:51], v[186:189], v[194:197], v[68:71]
	v_mfma_f32_16x16x32_bf16 v[56:59], v[180:183], v[206:209], v[56:59]
	v_mfma_f32_16x16x32_bf16 v[52:55], v[190:193], v[206:209], v[52:55]
	v_mfma_f32_16x16x32_bf16 v[24:27], v[180:183], v[214:217], v[24:27]
	v_mfma_f32_16x16x32_bf16 v[20:23], v[190:193], v[214:217], v[20:23]
	v_mfma_f32_16x16x32_bf16 v[8:11], v[180:183], v[222:225], v[8:11]
	v_mfma_f32_16x16x32_bf16 v[4:7], v[190:193], v[222:225], v[4:7]
	v_mfma_f32_16x16x32_bf16 v[44:47], v[180:183], v[198:201], v[44:47]
	v_mfma_f32_16x16x32_bf16 v[48:51], v[190:193], v[198:201], v[48:51]
	s_setprio 0
	s_barrier
	s_add_i32 s3, 0, 0x18000
	v_add_u32_e32 v38, s3, v167
	s_add_i32 s42, 0, 0x1c000
	ds_read_b128 v[68:71], v38
	ds_read_b128 v[72:75], v38 offset:1024
	ds_read_b128 v[160:163], v38 offset:2048
	ds_read_b128 v[172:175], v38 offset:3072
	v_add_u32_e32 v38, s42, v167
	ds_read_b128 v[176:179], v38
	ds_read_b128 v[180:183], v38 offset:1024
	ds_read_b128 v[186:189], v38 offset:2048
	ds_read_b128 v[190:193], v38 offset:3072
	s_add_u32 s30, s30, 0x80000
	s_addc_u32 s31, s31, 0
	s_mov_b32 m0, s52
	v_lshl_add_u64 v[38:39], s[30:31], 0, v[0:1]
	ds_read_b128 v[194:197], v171 offset:32768
	ds_read_b128 v[198:201], v171 offset:33792
	ds_read_b128 v[202:205], v171 offset:34816
	ds_read_b128 v[206:209], v171 offset:35840
	ds_read_b128 v[210:213], v171 offset:36864
	ds_read_b128 v[214:217], v171 offset:37888
	ds_read_b128 v[218:221], v171 offset:38912
	ds_read_b128 v[222:225], v171 offset:39936
	global_load_lds_dwordx4 v[38:39], off
	v_lshl_add_u64 v[38:39], s[30:31], 0, v[148:149]
	s_mov_b32 m0, s53
	s_nop 0
	global_load_lds_dwordx4 v[38:39], off
	s_waitcnt vmcnt(8)
	s_waitcnt lgkmcnt(0)
	s_setprio 1
	s_barrier
	v_mfma_f32_16x16x32_bf16 v[144:147], v[68:71], v[194:197], v[144:147]
	v_mfma_f32_16x16x32_bf16 v[140:143], v[160:163], v[194:197], v[140:143]
	v_mfma_f32_16x16x32_bf16 v[128:131], v[68:71], v[202:205], v[128:131]
	v_mfma_f32_16x16x32_bf16 v[124:127], v[160:163], v[202:205], v[124:127]
	v_mfma_f32_16x16x32_bf16 v[112:115], v[68:71], v[210:213], v[112:115]
	v_mfma_f32_16x16x32_bf16 v[108:111], v[160:163], v[210:213], v[108:111]
	v_mfma_f32_16x16x32_bf16 v[96:99], v[68:71], v[218:221], v[96:99]
	v_mfma_f32_16x16x32_bf16 v[92:95], v[160:163], v[218:221], v[92:95]
	v_mfma_f32_16x16x32_bf16 v[144:147], v[72:75], v[198:201], v[144:147]
	v_mfma_f32_16x16x32_bf16 v[140:143], v[172:175], v[198:201], v[140:143]
	v_mfma_f32_16x16x32_bf16 v[128:131], v[72:75], v[206:209], v[128:131]
	v_mfma_f32_16x16x32_bf16 v[124:127], v[172:175], v[206:209], v[124:127]
	v_mfma_f32_16x16x32_bf16 v[112:115], v[72:75], v[214:217], v[112:115]
	v_mfma_f32_16x16x32_bf16 v[108:111], v[172:175], v[214:217], v[108:111]
	v_mfma_f32_16x16x32_bf16 v[96:99], v[72:75], v[222:225], v[96:99]
	v_mfma_f32_16x16x32_bf16 v[92:95], v[172:175], v[222:225], v[92:95]
	s_setprio 0
	s_setprio 1
	v_mfma_f32_16x16x32_bf16 v[136:139], v[176:179], v[194:197], v[136:139]
	v_mfma_f32_16x16x32_bf16 v[132:135], v[186:189], v[194:197], v[132:135]
	v_mfma_f32_16x16x32_bf16 v[120:123], v[176:179], v[202:205], v[120:123]
	v_mfma_f32_16x16x32_bf16 v[116:119], v[186:189], v[202:205], v[116:119]
	v_mfma_f32_16x16x32_bf16 v[104:107], v[176:179], v[210:213], v[104:107]
	v_mfma_f32_16x16x32_bf16 v[100:103], v[186:189], v[210:213], v[100:103]
	v_mfma_f32_16x16x32_bf16 v[88:91], v[176:179], v[218:221], v[88:91]
	v_mfma_f32_16x16x32_bf16 v[84:87], v[186:189], v[218:221], v[84:87]
	v_mfma_f32_16x16x32_bf16 v[136:139], v[180:183], v[198:201], v[136:139]
	v_mfma_f32_16x16x32_bf16 v[132:135], v[190:193], v[198:201], v[132:135]
	v_mfma_f32_16x16x32_bf16 v[120:123], v[180:183], v[206:209], v[120:123]
	v_mfma_f32_16x16x32_bf16 v[116:119], v[190:193], v[206:209], v[116:119]
	v_mfma_f32_16x16x32_bf16 v[104:107], v[180:183], v[214:217], v[104:107]
	v_mfma_f32_16x16x32_bf16 v[100:103], v[190:193], v[214:217], v[100:103]
	v_mfma_f32_16x16x32_bf16 v[88:91], v[180:183], v[222:225], v[88:91]
	v_mfma_f32_16x16x32_bf16 v[84:87], v[190:193], v[222:225], v[84:87]
	s_setprio 0
	s_barrier
; #define PG8_STAGE(bufoff, gbase, voff) do { _Pragma("unroll") for (int _i = 0; _i < 2; ++_i) \
;         __builtin_amdgcn_global_load_lds((const unsigned*)((const char*)(gbase) + (voff)[_i]), (PG8_LAS unsigned*)(lds + (bufoff) + ldsw + _i * 8192), 16, 0, 0); } while (0)
; #define PG8_LDA(dst, b, h) do { _Pragma("unroll") for (int m = 0; m < 4; ++m) _Pragma("unroll") for (int k = 0; k < 2; ++k) dst[m][k] = *(const PG8_LAS bf16x8*)(lds + PG8_SA(b, h) + aoff + m * 2048 + k * 1024); } while (0)
; #define PG8_MMA(ai, bj, At, Bt) do { __builtin_amdgcn_s_setprio(1); _Pragma("unroll") for (int m = 0; m < 4; ++m) _Pragma("unroll") for (int n = 0; n < 2; ++n) _Pragma("unroll") for (int k = 0; k < 2; ++k) \
;         acc[ai][bj][m][n] = __builtin_amdgcn_mfma_f32_16x16x32_bf16(Bt[n][k], At[m][k], acc[ai][bj][m][n], 0, 0, 0); __builtin_amdgcn_s_setprio(0); } while (0)
; #define PG8_WAIT_V(n) asm volatile("s_waitcnt vmcnt(" #n ")" ::: "memory")
; #define PG8_WAIT_L(n) asm volatile("s_waitcnt lgkmcnt(" #n ")" ::: "memory")
; #define PG8_BAR __builtin_amdgcn_s_barrier()
; #define PG8_SCHED __builtin_amdgcn_sched_barrier(0)
; template <class Epi, class Sched, bool ALIGN_EPI = false, bool SP2 = false>
; __device__ __forceinline__ void gemm_phase(PG8_LAS unsigned char* lds, const Gemm g, const Sched& S, const Epi& E, const int tid) {
;     ...
;         for (int t = 0; t < nt; t += 2) {
;     ...
;             PG8_LDA(At, 1, 1); PG8_STAGE(PG8_SB(1, 0), b3, voffB); PG8_STAGE(PG8_SB(1, 1), b3 + hstep, voffB); PG8_STAGE(PG8_SA(1, 0), a3, voffA);
;             PG8_WAIT_V(8); PG8_WAIT_L(0); PG8_BAR; PG8_MMA(1, 0, At, B0); PG8_MMA(1, 1, At, B1); PG8_BAR; PG8_SCHED;
	s_add_i32 s3, s3, s44
	v_lshl_add_u64 v[38:39], v[164:165], 0, s[46:47]
	s_mov_b32 m0, s3
	ds_read_b128 v[194:197], v171 offset:49152
	ds_read_b128 v[198:201], v171 offset:50176
	ds_read_b128 v[202:205], v171 offset:51200
	ds_read_b128 v[206:209], v171 offset:52224
	ds_read_b128 v[210:213], v171 offset:53248
	ds_read_b128 v[214:217], v171 offset:54272
	ds_read_b128 v[218:221], v171 offset:55296
	ds_read_b128 v[222:225], v171 offset:56320
	global_load_lds_dwordx4 v[38:39], off
	s_add_i32 m0, s3, 0x2000
	s_add_u32 s28, s28, 0x80080
	v_lshl_add_u64 v[38:39], v[226:227], 0, s[46:47]
	s_addc_u32 s29, s29, 0
	s_add_i32 s3, s42, s44
	global_load_lds_dwordx4 v[38:39], off
	v_lshl_add_u64 v[38:39], s[28:29], 0, v[2:3]
	s_mov_b32 m0, s3
	s_nop 0
	global_load_lds_dwordx4 v[38:39], off
	v_lshl_add_u64 v[38:39], s[28:29], 0, v[150:151]
	s_add_i32 m0, s3, 0x2000
	s_nop 0
	global_load_lds_dwordx4 v[38:39], off
	v_lshl_add_u64 v[38:39], v[228:229], 0, s[46:47]
	s_mov_b32 m0, s5
	s_nop 0
	global_load_lds_dwordx4 v[38:39], off
	v_lshl_add_u64 v[38:39], v[230:231], 0, s[46:47]
	s_mov_b32 m0, s54
	s_nop 0
	global_load_lds_dwordx4 v[38:39], off
	s_waitcnt vmcnt(8)
	s_waitcnt lgkmcnt(0)
	s_setprio 1
	s_barrier
	v_mfma_f32_16x16x32_bf16 v[80:83], v[68:71], v[194:197], v[80:83]
	v_mfma_f32_16x16x32_bf16 v[76:79], v[160:163], v[194:197], v[76:79]
	v_mfma_f32_16x16x32_bf16 v[64:67], v[68:71], v[202:205], v[64:67]
	v_mfma_f32_16x16x32_bf16 v[60:63], v[160:163], v[202:205], v[60:63]
	v_mfma_f32_16x16x32_bf16 v[38:41], v[68:71], v[210:213], v[40:43]
	v_mfma_f32_16x16x32_bf16 v[34:37], v[160:163], v[210:213], v[34:37]
	v_mfma_f32_16x16x32_bf16 v[16:19], v[68:71], v[218:221], v[16:19]
	v_mfma_f32_16x16x32_bf16 v[12:15], v[160:163], v[218:221], v[12:15]
	v_mfma_f32_16x16x32_bf16 v[80:83], v[72:75], v[198:201], v[80:83]
	v_mfma_f32_16x16x32_bf16 v[76:79], v[172:175], v[198:201], v[76:79]
	v_mfma_f32_16x16x32_bf16 v[64:67], v[72:75], v[206:209], v[64:67]
	v_mfma_f32_16x16x32_bf16 v[60:63], v[172:175], v[206:209], v[60:63]
	v_mfma_f32_16x16x32_bf16 v[40:43], v[72:75], v[214:217], v[38:41]
	v_mfma_f32_16x16x32_bf16 v[36:39], v[172:175], v[214:217], v[34:37]
	v_mfma_f32_16x16x32_bf16 v[16:19], v[72:75], v[222:225], v[16:19]
	v_mfma_f32_16x16x32_bf16 v[12:15], v[172:175], v[222:225], v[12:15]
	s_setprio 0
	s_setprio 1
	v_mfma_f32_16x16x32_bf16 v[44:47], v[176:179], v[194:197], v[44:47]
	v_mfma_f32_16x16x32_bf16 v[72:75], v[180:183], v[198:201], v[44:47]
	v_mfma_f32_16x16x32_bf16 v[44:47], v[186:189], v[194:197], v[48:51]
	v_mfma_f32_16x16x32_bf16 v[68:71], v[190:193], v[198:201], v[44:47]
	v_mfma_f32_16x16x32_bf16 v[44:47], v[176:179], v[202:205], v[56:59]
	v_mfma_f32_16x16x32_bf16 v[56:59], v[180:183], v[206:209], v[44:47]
	v_mfma_f32_16x16x32_bf16 v[44:47], v[186:189], v[202:205], v[52:55]
	v_mfma_f32_16x16x32_bf16 v[24:27], v[176:179], v[210:213], v[24:27]
	v_mfma_f32_16x16x32_bf16 v[20:23], v[186:189], v[210:213], v[20:23]
	v_mfma_f32_16x16x32_bf16 v[8:11], v[176:179], v[218:221], v[8:11]
	v_mfma_f32_16x16x32_bf16 v[4:7], v[186:189], v[218:221], v[4:7]
	v_mfma_f32_16x16x32_bf16 v[52:55], v[190:193], v[206:209], v[44:47]
	v_mfma_f32_16x16x32_bf16 v[24:27], v[180:183], v[214:217], v[24:27]
	v_mfma_f32_16x16x32_bf16 v[20:23], v[190:193], v[214:217], v[20:23]
	v_mfma_f32_16x16x32_bf16 v[8:11], v[180:183], v[222:225], v[8:11]
	v_mfma_f32_16x16x32_bf16 v[4:7], v[190:193], v[222:225], v[4:7]
	s_setprio 0
	s_barrier
	s_add_i32 s50, s50, 2
	s_add_u32 s26, s26, 0x100
	s_addc_u32 s27, s27, 0
	s_add_u32 s23, s23, 0x100
	s_addc_u32 s25, s25, 0
	s_cmp_gt_u32 s50, 29
	s_cbranch_scc1 .LBB0_159

; #define PG8_STAGE(bufoff, gbase, voff) do { _Pragma("unroll") for (int _i = 0; _i < 2; ++_i) \
;         __builtin_amdgcn_global_load_lds((const unsigned*)((const char*)(gbase) + (voff)[_i]), (PG8_LAS unsigned*)(lds + (bufoff) + ldsw + _i * 8192), 16, 0, 0); } while (0)
; #define PG8_LDA(dst, b, h) do { _Pragma("unroll") for (int m = 0; m < 4; ++m) _Pragma("unroll") for (int k = 0; k < 2; ++k) dst[m][k] = *(const PG8_LAS bf16x8*)(lds + PG8_SA(b, h) + aoff + m * 2048 + k * 1024); } while (0)
; #define PG8_LDB(dst, b, h) do { _Pragma("unroll") for (int n = 0; n < 2; ++n) _Pragma("unroll") for (int k = 0; k < 2; ++k) dst[n][k] = *(const PG8_LAS bf16x8*)(lds + PG8_SB(b, h) + boff + n * 2048 + k * 1024); } while (0)
; #define PG8_MMA(ai, bj, At, Bt) do { __builtin_amdgcn_s_setprio(1); _Pragma("unroll") for (int m = 0; m < 4; ++m) _Pragma("unroll") for (int n = 0; n < 2; ++n) _Pragma("unroll") for (int k = 0; k < 2; ++k) \
;         acc[ai][bj][m][n] = __builtin_amdgcn_mfma_f32_16x16x32_bf16(Bt[n][k], At[m][k], acc[ai][bj][m][n], 0, 0, 0); __builtin_amdgcn_s_setprio(0); } while (0)
; #define PG8_WAIT_V(n) asm volatile("s_waitcnt vmcnt(" #n ")" ::: "memory")
; #define PG8_WAIT_L(n) asm volatile("s_waitcnt lgkmcnt(" #n ")" ::: "memory")
; template <class Epi, class Sched, bool ALIGN_EPI = false, bool SP2 = false>
; __device__ __forceinline__ void gemm_phase(PG8_LAS unsigned char* lds, const Gemm g, const Sched& S, const Epi& E, const int tid) {
;     ...
;             const char* a2 = last ? nA : cA + (size_t)(t + 2) * kstep; const char* b2 = last ? nB : cB + (size_t)(t + 2) * kstep;
;             const char* a3 = a2 + kstep; const char* b3 = b2 + kstep;
;             if (last && has_next) S.a_ready(nxt);
;             if (last) E.prefetch(lds + EPI_LDS_OFF + wid * 1024, cur, wr, wc, lane);
;             if constexpr (SP2) {
;             PG8_LDB(B0, 0, 0); PG8_LDB(B1, 0, 1); PG8_SCHED; PG8_LDA(At, 0, 0); PG8_STAGE(PG8_SA(1, 1), a1 + hstep, voffA);
;             PG8_WAIT_V(8); PG8_WAIT_L(0); PG8_BAR; PG8_MMA(0, 0, At, B0); PG8_MMA(0, 1, At, B1); PG8_BAR; PG8_SCHED;
;             PG8_LDA(At, 0, 1); PG8_STAGE(PG8_SB(0, 0), b2, voffB); PG8_STAGE(PG8_SB(0, 1), b2 + hstep, voffB); PG8_STAGE(PG8_SA(0, 0), a2, voffA);
;             PG8_WAIT_V(8); PG8_WAIT_L(0); PG8_BAR; PG8_MMA(1, 0, At, B0); PG8_MMA(1, 1, At, B1); PG8_BAR; PG8_SCHED;
.LBB0_228:
	s_add_u32 s22, s20, 0x100
	s_addc_u32 s23, s21, 0
	s_and_b64 s[24:25], s[24:25], exec
	s_cselect_b32 s27, s11, s23
	s_cselect_b32 s26, s10, s22
	s_cselect_b32 s25, s17, s75
	s_cselect_b32 s24, s16, s74
	s_add_i32 s42, 0, 0x10000
	s_add_i32 s43, 0, 0x14000
	v_add_u32_e32 v146, s42, v220
	v_add_u32_e32 v162, s43, v220
	ds_read_b128 v[134:137], v146
	ds_read_b128 v[138:141], v146 offset:1024
	ds_read_b128 v[142:145], v146 offset:2048
	ds_read_b128 v[146:149], v146 offset:3072
	ds_read_b128 v[150:153], v162
	ds_read_b128 v[154:157], v162 offset:1024
	ds_read_b128 v[158:161], v162 offset:2048
	ds_read_b128 v[172:175], v162 offset:3072
	v_lshl_add_u64 v[162:163], s[20:21], 0, v[168:169]
	s_add_i32 m0, s30, 0xc000
	ds_read_b128 v[176:179], v226
	ds_read_b128 v[186:189], v226 offset:1024
	ds_read_b128 v[190:193], v226 offset:2048
	ds_read_b128 v[194:197], v226 offset:3072
	ds_read_b128 v[198:201], v226 offset:4096
	ds_read_b128 v[202:205], v226 offset:5120
	ds_read_b128 v[206:209], v226 offset:6144
	ds_read_b128 v[210:213], v226 offset:7168
	global_load_lds_dwordx4 v[162:163], off
	v_lshl_add_u64 v[162:163], s[20:21], 0, v[170:171]
	s_add_i32 m0, s30, 0xe000
	s_nop 0
	global_load_lds_dwordx4 v[162:163], off
	s_waitcnt vmcnt(8)
	s_waitcnt lgkmcnt(0)
	s_setprio 1
	s_barrier
	v_mfma_f32_16x16x32_bf16 v[128:131], v[134:137], v[176:179], v[128:131]
	v_mfma_f32_16x16x32_bf16 v[124:127], v[142:145], v[176:179], v[124:127]
	v_mfma_f32_16x16x32_bf16 v[112:115], v[134:137], v[190:193], v[112:115]
	v_mfma_f32_16x16x32_bf16 v[108:111], v[142:145], v[190:193], v[108:111]
	v_mfma_f32_16x16x32_bf16 v[96:99], v[134:137], v[198:201], v[96:99]
	v_mfma_f32_16x16x32_bf16 v[92:95], v[142:145], v[198:201], v[92:95]
	v_mfma_f32_16x16x32_bf16 v[80:83], v[134:137], v[206:209], v[80:83]
	v_mfma_f32_16x16x32_bf16 v[76:79], v[142:145], v[206:209], v[76:79]
	v_mfma_f32_16x16x32_bf16 v[128:131], v[138:141], v[186:189], v[128:131]
	v_mfma_f32_16x16x32_bf16 v[124:127], v[146:149], v[186:189], v[124:127]
	v_mfma_f32_16x16x32_bf16 v[112:115], v[138:141], v[194:197], v[112:115]
	v_mfma_f32_16x16x32_bf16 v[108:111], v[146:149], v[194:197], v[108:111]
	v_mfma_f32_16x16x32_bf16 v[96:99], v[138:141], v[202:205], v[96:99]
	v_mfma_f32_16x16x32_bf16 v[92:95], v[146:149], v[202:205], v[92:95]
	v_mfma_f32_16x16x32_bf16 v[80:83], v[138:141], v[210:213], v[80:83]
	v_mfma_f32_16x16x32_bf16 v[76:79], v[146:149], v[210:213], v[76:79]
	s_setprio 0
	s_setprio 1
	v_mfma_f32_16x16x32_bf16 v[120:123], v[150:153], v[176:179], v[120:123]
	v_mfma_f32_16x16x32_bf16 v[116:119], v[158:161], v[176:179], v[116:119]
	v_mfma_f32_16x16x32_bf16 v[104:107], v[150:153], v[190:193], v[104:107]
	v_mfma_f32_16x16x32_bf16 v[100:103], v[158:161], v[190:193], v[100:103]
	v_mfma_f32_16x16x32_bf16 v[88:91], v[150:153], v[198:201], v[88:91]
	v_mfma_f32_16x16x32_bf16 v[84:87], v[158:161], v[198:201], v[84:87]
	v_mfma_f32_16x16x32_bf16 v[72:75], v[150:153], v[206:209], v[72:75]
	v_mfma_f32_16x16x32_bf16 v[68:71], v[158:161], v[206:209], v[68:71]
	v_mfma_f32_16x16x32_bf16 v[120:123], v[154:157], v[186:189], v[120:123]
	v_mfma_f32_16x16x32_bf16 v[116:119], v[172:175], v[186:189], v[116:119]
	v_mfma_f32_16x16x32_bf16 v[104:107], v[154:157], v[194:197], v[104:107]
	v_mfma_f32_16x16x32_bf16 v[100:103], v[172:175], v[194:197], v[100:103]
	v_mfma_f32_16x16x32_bf16 v[88:91], v[154:157], v[202:205], v[88:91]
	v_mfma_f32_16x16x32_bf16 v[84:87], v[172:175], v[202:205], v[84:87]
	v_mfma_f32_16x16x32_bf16 v[72:75], v[154:157], v[210:213], v[72:75]
	v_mfma_f32_16x16x32_bf16 v[68:71], v[172:175], v[210:213], v[68:71]
	s_setprio 0
	s_barrier
	s_add_i32 s20, s42, s29
	v_lshl_add_u64 v[162:163], s[24:25], 0, v[2:3]
	s_mov_b32 m0, s20
	ds_read_b128 v[176:179], v226 offset:16384
	ds_read_b128 v[186:189], v226 offset:17408
	ds_read_b128 v[190:193], v226 offset:18432
	ds_read_b128 v[194:197], v226 offset:19456
	ds_read_b128 v[198:201], v226 offset:20480
	ds_read_b128 v[202:205], v226 offset:21504
	ds_read_b128 v[206:209], v226 offset:22528
	ds_read_b128 v[210:213], v226 offset:23552
	global_load_lds_dwordx4 v[162:163], off
	s_add_i32 m0, s20, 0x2000
	s_add_u32 s20, s24, 0x160000
	v_lshl_add_u64 v[180:181], s[24:25], 0, v[166:167]
	s_addc_u32 s21, s25, 0
	s_add_i32 s42, s43, s29
	global_load_lds_dwordx4 v[180:181], off
	v_lshl_add_u64 v[182:183], s[20:21], 0, v[2:3]
	s_mov_b32 m0, s42
	v_lshl_add_u64 v[214:215], s[26:27], 0, v[164:165]
	global_load_lds_dwordx4 v[182:183], off
	v_lshl_add_u64 v[182:183], s[20:21], 0, v[166:167]
	s_add_i32 m0, s42, 0x2000
	s_nop 0
	global_load_lds_dwordx4 v[182:183], off
	v_lshl_add_u64 v[182:183], s[26:27], 0, v[0:1]
	s_mov_b32 m0, s30
	s_nop 0
	global_load_lds_dwordx4 v[182:183], off
	s_mov_b32 m0, s31
	s_nop 0
	global_load_lds_dwordx4 v[214:215], off
	s_waitcnt vmcnt(8)
	s_waitcnt lgkmcnt(0)
	s_setprio 1
	s_barrier
; #define PG8_STAGE(bufoff, gbase, voff) do { _Pragma("unroll") for (int _i = 0; _i < 2; ++_i) \
;         __builtin_amdgcn_global_load_lds((const unsigned*)((const char*)(gbase) + (voff)[_i]), (PG8_LAS unsigned*)(lds + (bufoff) + ldsw + _i * 8192), 16, 0, 0); } while (0)
; #define PG8_LDA(dst, b, h) do { _Pragma("unroll") for (int m = 0; m < 4; ++m) _Pragma("unroll") for (int k = 0; k < 2; ++k) dst[m][k] = *(const PG8_LAS bf16x8*)(lds + PG8_SA(b, h) + aoff + m * 2048 + k * 1024); } while (0)
; #define PG8_LDB(dst, b, h) do { _Pragma("unroll") for (int n = 0; n < 2; ++n) _Pragma("unroll") for (int k = 0; k < 2; ++k) dst[n][k] = *(const PG8_LAS bf16x8*)(lds + PG8_SB(b, h) + boff + n * 2048 + k * 1024); } while (0)
; #define PG8_MMA(ai, bj, At, Bt) do { __builtin_amdgcn_s_setprio(1); _Pragma("unroll") for (int m = 0; m < 4; ++m) _Pragma("unroll") for (int n = 0; n < 2; ++n) _Pragma("unroll") for (int k = 0; k < 2; ++k) \
;         acc[ai][bj][m][n] = __builtin_amdgcn_mfma_f32_16x16x32_bf16(Bt[n][k], At[m][k], acc[ai][bj][m][n], 0, 0, 0); __builtin_amdgcn_s_setprio(0); } while (0)
; #define PG8_WAIT_V(n) asm volatile("s_waitcnt vmcnt(" #n ")" ::: "memory")
; #define PG8_WAIT_L(n) asm volatile("s_waitcnt lgkmcnt(" #n ")" ::: "memory")
; #define PG8_BAR __builtin_amdgcn_s_barrier()
; #define PG8_SCHED __builtin_amdgcn_sched_barrier(0)
; template <class Epi, class Sched, bool ALIGN_EPI = false, bool SP2 = false>
; __device__ __forceinline__ void gemm_phase(PG8_LAS unsigned char* lds, const Gemm g, const Sched& S, const Epi& E, const int tid) {
;     ...
;             PG8_WAIT_V(8); PG8_WAIT_L(0); PG8_BAR; PG8_MMA(1, 0, At, B0); PG8_MMA(1, 1, At, B1); PG8_BAR; PG8_SCHED;
;             PG8_LDB(B0, 1, 0); PG8_LDB(B1, 1, 1); PG8_SCHED; PG8_LDA(At, 1, 0); PG8_STAGE(PG8_SA(0, 1), a2 + hstep, voffA);
;             PG8_WAIT_V(8); PG8_WAIT_L(0); PG8_BAR; PG8_MMA(0, 0, At, B0); PG8_MMA(0, 1, At, B1); PG8_BAR; PG8_SCHED;
	v_mfma_f32_16x16x32_bf16 v[64:67], v[134:137], v[176:179], v[64:67]
	v_mfma_f32_16x16x32_bf16 v[60:63], v[142:145], v[176:179], v[60:63]
	v_mfma_f32_16x16x32_bf16 v[48:51], v[134:137], v[190:193], v[48:51]
	v_mfma_f32_16x16x32_bf16 v[44:47], v[142:145], v[190:193], v[44:47]
	v_mfma_f32_16x16x32_bf16 v[32:35], v[134:137], v[198:201], v[32:35]
	v_mfma_f32_16x16x32_bf16 v[28:31], v[142:145], v[198:201], v[28:31]
	v_mfma_f32_16x16x32_bf16 v[16:19], v[134:137], v[206:209], v[16:19]
	v_mfma_f32_16x16x32_bf16 v[12:15], v[142:145], v[206:209], v[12:15]
	v_mfma_f32_16x16x32_bf16 v[64:67], v[138:141], v[186:189], v[64:67]
	v_mfma_f32_16x16x32_bf16 v[60:63], v[146:149], v[186:189], v[60:63]
	v_mfma_f32_16x16x32_bf16 v[48:51], v[138:141], v[194:197], v[48:51]
	v_mfma_f32_16x16x32_bf16 v[44:47], v[146:149], v[194:197], v[44:47]
	v_mfma_f32_16x16x32_bf16 v[32:35], v[138:141], v[202:205], v[32:35]
	v_mfma_f32_16x16x32_bf16 v[28:31], v[146:149], v[202:205], v[28:31]
	v_mfma_f32_16x16x32_bf16 v[16:19], v[138:141], v[210:213], v[16:19]
	v_mfma_f32_16x16x32_bf16 v[12:15], v[146:149], v[210:213], v[12:15]
	s_setprio 0
	s_setprio 1
	v_mfma_f32_16x16x32_bf16 v[56:59], v[150:153], v[176:179], v[56:59]
	v_mfma_f32_16x16x32_bf16 v[52:55], v[158:161], v[176:179], v[52:55]
	v_mfma_f32_16x16x32_bf16 v[40:43], v[150:153], v[190:193], v[40:43]
	v_mfma_f32_16x16x32_bf16 v[36:39], v[158:161], v[190:193], v[36:39]
	v_mfma_f32_16x16x32_bf16 v[24:27], v[150:153], v[198:201], v[24:27]
	v_mfma_f32_16x16x32_bf16 v[20:23], v[158:161], v[198:201], v[20:23]
	v_mfma_f32_16x16x32_bf16 v[8:11], v[150:153], v[206:209], v[8:11]
	v_mfma_f32_16x16x32_bf16 v[4:7], v[158:161], v[206:209], v[4:7]
	v_mfma_f32_16x16x32_bf16 v[56:59], v[154:157], v[186:189], v[56:59]
	v_mfma_f32_16x16x32_bf16 v[52:55], v[172:175], v[186:189], v[52:55]
	v_mfma_f32_16x16x32_bf16 v[40:43], v[154:157], v[194:197], v[40:43]
	v_mfma_f32_16x16x32_bf16 v[36:39], v[172:175], v[194:197], v[36:39]
	v_mfma_f32_16x16x32_bf16 v[24:27], v[154:157], v[202:205], v[24:27]
	v_mfma_f32_16x16x32_bf16 v[20:23], v[172:175], v[202:205], v[20:23]
	v_mfma_f32_16x16x32_bf16 v[8:11], v[154:157], v[210:213], v[8:11]
	v_mfma_f32_16x16x32_bf16 v[4:7], v[172:175], v[210:213], v[4:7]
	s_setprio 0
	s_barrier
	s_add_i32 s42, 0, 0x18000
	s_add_i32 s43, 0, 0x1c000
	v_add_u32_e32 v146, s42, v220
	v_add_u32_e32 v172, s43, v220
	ds_read_b128 v[134:137], v146
	ds_read_b128 v[138:141], v146 offset:1024
	ds_read_b128 v[142:145], v146 offset:2048
	ds_read_b128 v[146:149], v146 offset:3072
	ds_read_b128 v[150:153], v172
	ds_read_b128 v[154:157], v172 offset:1024
	ds_read_b128 v[158:161], v172 offset:2048
	ds_read_b128 v[172:175], v172 offset:3072
	s_add_u32 s20, s26, 0x160000
	s_addc_u32 s21, s27, 0
	s_mov_b32 m0, s36
	v_lshl_add_u64 v[216:217], s[20:21], 0, v[0:1]
	ds_read_b128 v[176:179], v226 offset:32768
	ds_read_b128 v[186:189], v226 offset:33792
	ds_read_b128 v[190:193], v226 offset:34816
	ds_read_b128 v[194:197], v226 offset:35840
	ds_read_b128 v[198:201], v226 offset:36864
	ds_read_b128 v[202:205], v226 offset:37888
	ds_read_b128 v[206:209], v226 offset:38912
	ds_read_b128 v[210:213], v226 offset:39936
	global_load_lds_dwordx4 v[216:217], off
	v_lshl_add_u64 v[216:217], s[20:21], 0, v[164:165]
	s_mov_b32 m0, s37
	s_nop 0
	global_load_lds_dwordx4 v[216:217], off
	s_waitcnt vmcnt(8)
	s_waitcnt lgkmcnt(0)
	s_setprio 1
	s_barrier
	v_mfma_f32_16x16x32_bf16 v[128:131], v[134:137], v[176:179], v[128:131]
	v_mfma_f32_16x16x32_bf16 v[124:127], v[142:145], v[176:179], v[124:127]
	v_mfma_f32_16x16x32_bf16 v[112:115], v[134:137], v[190:193], v[112:115]
	v_mfma_f32_16x16x32_bf16 v[108:111], v[142:145], v[190:193], v[108:111]
	v_mfma_f32_16x16x32_bf16 v[96:99], v[134:137], v[198:201], v[96:99]
	v_mfma_f32_16x16x32_bf16 v[92:95], v[142:145], v[198:201], v[92:95]
	v_mfma_f32_16x16x32_bf16 v[80:83], v[134:137], v[206:209], v[80:83]
	v_mfma_f32_16x16x32_bf16 v[76:79], v[142:145], v[206:209], v[76:79]
	v_mfma_f32_16x16x32_bf16 v[128:131], v[138:141], v[186:189], v[128:131]
	v_mfma_f32_16x16x32_bf16 v[124:127], v[146:149], v[186:189], v[124:127]
	v_mfma_f32_16x16x32_bf16 v[112:115], v[138:141], v[194:197], v[112:115]
	v_mfma_f32_16x16x32_bf16 v[108:111], v[146:149], v[194:197], v[108:111]
	v_mfma_f32_16x16x32_bf16 v[96:99], v[138:141], v[202:205], v[96:99]
	v_mfma_f32_16x16x32_bf16 v[92:95], v[146:149], v[202:205], v[92:95]
	v_mfma_f32_16x16x32_bf16 v[80:83], v[138:141], v[210:213], v[80:83]
	v_mfma_f32_16x16x32_bf16 v[76:79], v[146:149], v[210:213], v[76:79]
	s_setprio 0
	s_setprio 1
	v_mfma_f32_16x16x32_bf16 v[120:123], v[150:153], v[176:179], v[120:123]
	v_mfma_f32_16x16x32_bf16 v[116:119], v[158:161], v[176:179], v[116:119]
	v_mfma_f32_16x16x32_bf16 v[104:107], v[150:153], v[190:193], v[104:107]
	v_mfma_f32_16x16x32_bf16 v[100:103], v[158:161], v[190:193], v[100:103]
	v_mfma_f32_16x16x32_bf16 v[88:91], v[150:153], v[198:201], v[88:91]
	v_mfma_f32_16x16x32_bf16 v[84:87], v[158:161], v[198:201], v[84:87]
	v_mfma_f32_16x16x32_bf16 v[72:75], v[150:153], v[206:209], v[72:75]
	v_mfma_f32_16x16x32_bf16 v[68:71], v[158:161], v[206:209], v[68:71]
	v_mfma_f32_16x16x32_bf16 v[120:123], v[154:157], v[186:189], v[120:123]
	v_mfma_f32_16x16x32_bf16 v[116:119], v[172:175], v[186:189], v[116:119]
	v_mfma_f32_16x16x32_bf16 v[104:107], v[154:157], v[194:197], v[104:107]
	v_mfma_f32_16x16x32_bf16 v[100:103], v[172:175], v[194:197], v[100:103]
	v_mfma_f32_16x16x32_bf16 v[88:91], v[154:157], v[202:205], v[88:91]
	v_mfma_f32_16x16x32_bf16 v[84:87], v[172:175], v[202:205], v[84:87]
	v_mfma_f32_16x16x32_bf16 v[72:75], v[154:157], v[210:213], v[72:75]
	v_mfma_f32_16x16x32_bf16 v[68:71], v[172:175], v[210:213], v[68:71]
	s_setprio 0
	s_barrier
; #define PG8_STAGE(bufoff, gbase, voff) do { _Pragma("unroll") for (int _i = 0; _i < 2; ++_i) \
;         __builtin_amdgcn_global_load_lds((const unsigned*)((const char*)(gbase) + (voff)[_i]), (PG8_LAS unsigned*)(lds + (bufoff) + ldsw + _i * 8192), 16, 0, 0); } while (0)
; #define PG8_LDA(dst, b, h) do { _Pragma("unroll") for (int m = 0; m < 4; ++m) _Pragma("unroll") for (int k = 0; k < 2; ++k) dst[m][k] = *(const PG8_LAS bf16x8*)(lds + PG8_SA(b, h) + aoff + m * 2048 + k * 1024); } while (0)
; #define PG8_MMA(ai, bj, At, Bt) do { __builtin_amdgcn_s_setprio(1); _Pragma("unroll") for (int m = 0; m < 4; ++m) _Pragma("unroll") for (int n = 0; n < 2; ++n) _Pragma("unroll") for (int k = 0; k < 2; ++k) \
;         acc[ai][bj][m][n] = __builtin_amdgcn_mfma_f32_16x16x32_bf16(Bt[n][k], At[m][k], acc[ai][bj][m][n], 0, 0, 0); __builtin_amdgcn_s_setprio(0); } while (0)
; #define PG8_WAIT_V(n) asm volatile("s_waitcnt vmcnt(" #n ")" ::: "memory")
; #define PG8_WAIT_L(n) asm volatile("s_waitcnt lgkmcnt(" #n ")" ::: "memory")
; #define PG8_BAR __builtin_amdgcn_s_barrier()
; #define PG8_SCHED __builtin_amdgcn_sched_barrier(0)
; template <class Epi, class Sched, bool ALIGN_EPI = false, bool SP2 = false>
; __device__ __forceinline__ void gemm_phase(PG8_LAS unsigned char* lds, const Gemm g, const Sched& S, const Epi& E, const int tid) {
;     ...
;         for (int t = 0; t < nt; t += 2) {
;     ...
;             PG8_LDA(At, 1, 1); PG8_STAGE(PG8_SB(1, 0), b3, voffB); PG8_STAGE(PG8_SB(1, 1), b3 + hstep, voffB); PG8_STAGE(PG8_SA(1, 0), a3, voffA);
;             PG8_WAIT_V(8); PG8_WAIT_L(0); PG8_BAR; PG8_MMA(1, 0, At, B0); PG8_MMA(1, 1, At, B1); PG8_BAR; PG8_SCHED;
	s_add_i32 s20, s42, s29
	v_lshl_add_u64 v[162:163], v[162:163], 0, s[46:47]
	s_mov_b32 m0, s20
	ds_read_b128 v[176:179], v226 offset:49152
	ds_read_b128 v[186:189], v226 offset:50176
	ds_read_b128 v[190:193], v226 offset:51200
	ds_read_b128 v[194:197], v226 offset:52224
	ds_read_b128 v[198:201], v226 offset:53248
	ds_read_b128 v[202:205], v226 offset:54272
	ds_read_b128 v[206:209], v226 offset:55296
	ds_read_b128 v[210:213], v226 offset:56320
	global_load_lds_dwordx4 v[162:163], off
	s_add_i32 m0, s20, 0x2000
	s_add_u32 s20, s24, 0x160080
	v_lshl_add_u64 v[162:163], v[180:181], 0, s[46:47]
	s_addc_u32 s21, s25, 0
	s_add_i32 s24, s43, s29
	global_load_lds_dwordx4 v[162:163], off
	v_lshl_add_u64 v[162:163], s[20:21], 0, v[2:3]
	s_mov_b32 m0, s24
	s_nop 0
	global_load_lds_dwordx4 v[162:163], off
	v_lshl_add_u64 v[162:163], s[20:21], 0, v[166:167]
	s_add_i32 m0, s24, 0x2000
	s_nop 0
	global_load_lds_dwordx4 v[162:163], off
	v_lshl_add_u64 v[162:163], v[182:183], 0, s[46:47]
	s_mov_b32 m0, s39
	s_nop 0
	global_load_lds_dwordx4 v[162:163], off
	v_lshl_add_u64 v[162:163], v[214:215], 0, s[46:47]
	s_mov_b32 m0, s44
	s_nop 0
	global_load_lds_dwordx4 v[162:163], off
	s_waitcnt vmcnt(8)
	s_waitcnt lgkmcnt(0)
	s_setprio 1
	s_barrier
	v_mfma_f32_16x16x32_bf16 v[64:67], v[134:137], v[176:179], v[64:67]
	v_mfma_f32_16x16x32_bf16 v[60:63], v[142:145], v[176:179], v[60:63]
	v_mfma_f32_16x16x32_bf16 v[48:51], v[134:137], v[190:193], v[48:51]
	v_mfma_f32_16x16x32_bf16 v[44:47], v[142:145], v[190:193], v[44:47]
	v_mfma_f32_16x16x32_bf16 v[32:35], v[134:137], v[198:201], v[32:35]
	v_mfma_f32_16x16x32_bf16 v[28:31], v[142:145], v[198:201], v[28:31]
	v_mfma_f32_16x16x32_bf16 v[16:19], v[134:137], v[206:209], v[16:19]
	v_mfma_f32_16x16x32_bf16 v[12:15], v[142:145], v[206:209], v[12:15]
	v_mfma_f32_16x16x32_bf16 v[64:67], v[138:141], v[186:189], v[64:67]
	v_mfma_f32_16x16x32_bf16 v[60:63], v[146:149], v[186:189], v[60:63]
	v_mfma_f32_16x16x32_bf16 v[48:51], v[138:141], v[194:197], v[48:51]
	v_mfma_f32_16x16x32_bf16 v[44:47], v[146:149], v[194:197], v[44:47]
	v_mfma_f32_16x16x32_bf16 v[32:35], v[138:141], v[202:205], v[32:35]
	v_mfma_f32_16x16x32_bf16 v[28:31], v[146:149], v[202:205], v[28:31]
	v_mfma_f32_16x16x32_bf16 v[16:19], v[138:141], v[210:213], v[16:19]
	v_mfma_f32_16x16x32_bf16 v[12:15], v[146:149], v[210:213], v[12:15]
	s_setprio 0
	s_setprio 1
	v_mfma_f32_16x16x32_bf16 v[56:59], v[150:153], v[176:179], v[56:59]
	v_mfma_f32_16x16x32_bf16 v[52:55], v[158:161], v[176:179], v[52:55]
	v_mfma_f32_16x16x32_bf16 v[40:43], v[150:153], v[190:193], v[40:43]
	v_mfma_f32_16x16x32_bf16 v[36:39], v[158:161], v[190:193], v[36:39]
	v_mfma_f32_16x16x32_bf16 v[24:27], v[150:153], v[198:201], v[24:27]
	v_mfma_f32_16x16x32_bf16 v[20:23], v[158:161], v[198:201], v[20:23]
	v_mfma_f32_16x16x32_bf16 v[8:11], v[150:153], v[206:209], v[8:11]
	v_mfma_f32_16x16x32_bf16 v[4:7], v[158:161], v[206:209], v[4:7]
	v_mfma_f32_16x16x32_bf16 v[56:59], v[154:157], v[186:189], v[56:59]
	v_mfma_f32_16x16x32_bf16 v[52:55], v[172:175], v[186:189], v[52:55]
	v_mfma_f32_16x16x32_bf16 v[40:43], v[154:157], v[194:197], v[40:43]
	v_mfma_f32_16x16x32_bf16 v[36:39], v[172:175], v[194:197], v[36:39]
	v_mfma_f32_16x16x32_bf16 v[24:27], v[154:157], v[202:205], v[24:27]
	v_mfma_f32_16x16x32_bf16 v[20:23], v[172:175], v[202:205], v[20:23]
	v_mfma_f32_16x16x32_bf16 v[8:11], v[154:157], v[210:213], v[8:11]
	v_mfma_f32_16x16x32_bf16 v[4:7], v[172:175], v[210:213], v[4:7]
	s_setprio 0
	s_barrier
	s_add_i32 s84, s84, 2
	s_add_u32 s74, s74, 0x100
	s_addc_u32 s75, s75, 0
	s_cmpk_gt_u32 s84, 0x55
	s_mov_b64 s[20:21], s[22:23]
	s_cbranch_scc1 .LBB0_231

; #define PG8_STAGE(bufoff, gbase, voff) do { _Pragma("unroll") for (int _i = 0; _i < 2; ++_i) \
;         __builtin_amdgcn_global_load_lds((const unsigned*)((const char*)(gbase) + (voff)[_i]), (PG8_LAS unsigned*)(lds + (bufoff) + ldsw + _i * 8192), 16, 0, 0); } while (0)
; #define PG8_LDA(dst, b, h) do { _Pragma("unroll") for (int m = 0; m < 4; ++m) _Pragma("unroll") for (int k = 0; k < 2; ++k) dst[m][k] = *(const PG8_LAS bf16x8*)(lds + PG8_SA(b, h) + aoff + m * 2048 + k * 1024); } while (0)
; #define PG8_LDB(dst, b, h) do { _Pragma("unroll") for (int n = 0; n < 2; ++n) _Pragma("unroll") for (int k = 0; k < 2; ++k) dst[n][k] = *(const PG8_LAS bf16x8*)(lds + PG8_SB(b, h) + boff + n * 2048 + k * 1024); } while (0)
; #define PG8_MMA(ai, bj, At, Bt) do { __builtin_amdgcn_s_setprio(1); _Pragma("unroll") for (int m = 0; m < 4; ++m) _Pragma("unroll") for (int n = 0; n < 2; ++n) _Pragma("unroll") for (int k = 0; k < 2; ++k) \
;         acc[ai][bj][m][n] = __builtin_amdgcn_mfma_f32_16x16x32_bf16(Bt[n][k], At[m][k], acc[ai][bj][m][n], 0, 0, 0); __builtin_amdgcn_s_setprio(0); } while (0)
; #define PG8_WAIT_V(n) asm volatile("s_waitcnt vmcnt(" #n ")" ::: "memory")
; #define PG8_WAIT_L(n) asm volatile("s_waitcnt lgkmcnt(" #n ")" ::: "memory")
; template <class Epi, class Sched, bool ALIGN_EPI = false, bool SP2 = false>
; __device__ __forceinline__ void gemm_phase(PG8_LAS unsigned char* lds, const Gemm g, const Sched& S, const Epi& E, const int tid) {
;     ...
;             const char* a2 = last ? nA : cA + (size_t)(t + 2) * kstep; const char* b2 = last ? nB : cB + (size_t)(t + 2) * kstep;
;             const char* a3 = a2 + kstep; const char* b3 = b2 + kstep;
;             if (last && has_next) S.a_ready(nxt);
;             if (last) E.prefetch(lds + EPI_LDS_OFF + wid * 1024, cur, wr, wc, lane);
;             if constexpr (SP2) {
;             PG8_LDB(B0, 0, 0); PG8_LDB(B1, 0, 1); PG8_SCHED; PG8_LDA(At, 0, 0); PG8_STAGE(PG8_SA(1, 1), a1 + hstep, voffA);
;             PG8_WAIT_V(8); PG8_WAIT_L(0); PG8_BAR; PG8_MMA(0, 0, At, B0); PG8_MMA(0, 1, At, B1); PG8_BAR; PG8_SCHED;
;             PG8_LDA(At, 0, 1); PG8_STAGE(PG8_SB(0, 0), b2, voffB); PG8_STAGE(PG8_SB(0, 1), b2 + hstep, voffB); PG8_STAGE(PG8_SA(0, 0), a2, voffA);
;             PG8_WAIT_V(8); PG8_WAIT_L(0); PG8_BAR; PG8_MMA(1, 0, At, B0); PG8_MMA(1, 1, At, B1); PG8_BAR; PG8_SCHED;
.LBB0_266:
	s_add_u32 s28, s24, 0xfff80080
	s_addc_u32 s29, s25, -1
	s_and_b64 s[26:27], s[26:27], exec
	s_cselect_b32 s29, s17, s29
	s_cselect_b32 s28, s75, s28
	s_cselect_b32 s27, s15, s50
	s_cselect_b32 s26, s85, s23
	s_add_i32 s42, 0, 0x10000
	v_add_u32_e32 v134, s42, v161
	s_add_i32 s43, 0, 0x14000
	ds_read_b128 v[140:143], v134
	ds_read_b128 v[144:147], v134 offset:1024
	ds_read_b128 v[166:169], v134 offset:2048
	ds_read_b128 v[170:173], v134 offset:3072
	v_add_u32_e32 v134, s43, v161
	ds_read_b128 v[174:177], v134
	ds_read_b128 v[186:189], v134 offset:1024
	ds_read_b128 v[190:193], v134 offset:2048
	ds_read_b128 v[194:197], v134 offset:3072
	v_lshl_add_u64 v[134:135], s[24:25], 0, v[156:157]
	s_add_i32 m0, s37, 0xc000
	ds_read_b128 v[198:201], v165
	ds_read_b128 v[202:205], v165 offset:1024
	ds_read_b128 v[206:209], v165 offset:2048
	ds_read_b128 v[210:213], v165 offset:3072
	ds_read_b128 v[214:217], v165 offset:4096
	ds_read_b128 v[218:221], v165 offset:5120
	ds_read_b128 v[222:225], v165 offset:6144
	ds_read_b128 v[226:229], v165 offset:7168
	global_load_lds_dwordx4 v[134:135], off
	v_lshl_add_u64 v[134:135], s[24:25], 0, v[158:159]
	s_add_i32 m0, s37, 0xe000
	s_nop 0
	global_load_lds_dwordx4 v[134:135], off
	s_waitcnt vmcnt(8)
	s_waitcnt lgkmcnt(0)
	s_setprio 1
	s_barrier
	v_mfma_f32_16x16x32_bf16 v[134:137], v[140:143], v[198:201], v[136:139]
	v_mfma_f32_16x16x32_bf16 v[124:127], v[166:169], v[198:201], v[124:127]
	v_mfma_f32_16x16x32_bf16 v[112:115], v[140:143], v[206:209], v[112:115]
	v_mfma_f32_16x16x32_bf16 v[108:111], v[166:169], v[206:209], v[108:111]
	v_mfma_f32_16x16x32_bf16 v[96:99], v[140:143], v[214:217], v[96:99]
	v_mfma_f32_16x16x32_bf16 v[92:95], v[166:169], v[214:217], v[92:95]
	v_mfma_f32_16x16x32_bf16 v[80:83], v[140:143], v[222:225], v[80:83]
	v_mfma_f32_16x16x32_bf16 v[76:79], v[166:169], v[222:225], v[76:79]
	v_mfma_f32_16x16x32_bf16 v[134:137], v[144:147], v[202:205], v[134:137]
	v_mfma_f32_16x16x32_bf16 v[124:127], v[170:173], v[202:205], v[124:127]
	v_mfma_f32_16x16x32_bf16 v[112:115], v[144:147], v[210:213], v[112:115]
	v_mfma_f32_16x16x32_bf16 v[108:111], v[170:173], v[210:213], v[108:111]
	v_mfma_f32_16x16x32_bf16 v[96:99], v[144:147], v[218:221], v[96:99]
	v_mfma_f32_16x16x32_bf16 v[92:95], v[170:173], v[218:221], v[92:95]
	v_mfma_f32_16x16x32_bf16 v[80:83], v[144:147], v[226:229], v[80:83]
	v_mfma_f32_16x16x32_bf16 v[76:79], v[170:173], v[226:229], v[76:79]
	s_setprio 0
	s_setprio 1
	v_mfma_f32_16x16x32_bf16 v[120:123], v[174:177], v[198:201], v[120:123]
	v_mfma_f32_16x16x32_bf16 v[116:119], v[190:193], v[198:201], v[116:119]
	v_mfma_f32_16x16x32_bf16 v[104:107], v[174:177], v[206:209], v[104:107]
	v_mfma_f32_16x16x32_bf16 v[100:103], v[190:193], v[206:209], v[100:103]
	v_mfma_f32_16x16x32_bf16 v[88:91], v[174:177], v[214:217], v[88:91]
	v_mfma_f32_16x16x32_bf16 v[84:87], v[190:193], v[214:217], v[84:87]
	v_mfma_f32_16x16x32_bf16 v[72:75], v[174:177], v[222:225], v[72:75]
	v_mfma_f32_16x16x32_bf16 v[68:71], v[190:193], v[222:225], v[68:71]
	v_mfma_f32_16x16x32_bf16 v[120:123], v[186:189], v[202:205], v[120:123]
	v_mfma_f32_16x16x32_bf16 v[116:119], v[194:197], v[202:205], v[116:119]
	v_mfma_f32_16x16x32_bf16 v[104:107], v[186:189], v[210:213], v[104:107]
	v_mfma_f32_16x16x32_bf16 v[100:103], v[194:197], v[210:213], v[100:103]
	v_mfma_f32_16x16x32_bf16 v[88:91], v[186:189], v[218:221], v[88:91]
	v_mfma_f32_16x16x32_bf16 v[84:87], v[194:197], v[218:221], v[84:87]
	v_mfma_f32_16x16x32_bf16 v[72:75], v[186:189], v[226:229], v[72:75]
	v_mfma_f32_16x16x32_bf16 v[68:71], v[194:197], v[226:229], v[68:71]
	s_setprio 0
	s_barrier
	s_add_i32 s42, s42, s31
	v_lshl_add_u64 v[178:179], s[26:27], 0, v[2:3]
	s_mov_b32 m0, s42
	ds_read_b128 v[198:201], v165 offset:16384
	ds_read_b128 v[202:205], v165 offset:17408
	ds_read_b128 v[206:209], v165 offset:18432
	ds_read_b128 v[210:213], v165 offset:19456
	ds_read_b128 v[214:217], v165 offset:20480
	ds_read_b128 v[218:221], v165 offset:21504
	ds_read_b128 v[222:225], v165 offset:22528
	ds_read_b128 v[226:229], v165 offset:23552
	global_load_lds_dwordx4 v[178:179], off
	s_add_i32 m0, s42, 0x2000
	s_add_u32 s94, s26, 0x80000
	v_lshl_add_u64 v[180:181], s[26:27], 0, v[0:1]
	s_addc_u32 s95, s27, 0
	s_add_i32 s42, s43, s31
	global_load_lds_dwordx4 v[180:181], off
	v_lshl_add_u64 v[138:139], s[94:95], 0, v[2:3]
	s_mov_b32 m0, s42
	v_lshl_add_u64 v[182:183], s[28:29], 0, v[150:151]
	global_load_lds_dwordx4 v[138:139], off
	v_lshl_add_u64 v[138:139], s[94:95], 0, v[0:1]
	s_add_i32 m0, s42, 0x2000
	v_lshl_add_u64 v[230:231], s[28:29], 0, v[148:149]
	global_load_lds_dwordx4 v[138:139], off
	s_mov_b32 m0, s37
	s_nop 0
	global_load_lds_dwordx4 v[182:183], off
	s_mov_b32 m0, s39
	s_nop 0
	global_load_lds_dwordx4 v[230:231], off
	s_waitcnt vmcnt(8)
	s_waitcnt lgkmcnt(0)
	s_setprio 1
	s_barrier
; #define PG8_STAGE(bufoff, gbase, voff) do { _Pragma("unroll") for (int _i = 0; _i < 2; ++_i) \
;         __builtin_amdgcn_global_load_lds((const unsigned*)((const char*)(gbase) + (voff)[_i]), (PG8_LAS unsigned*)(lds + (bufoff) + ldsw + _i * 8192), 16, 0, 0); } while (0)
; #define PG8_LDA(dst, b, h) do { _Pragma("unroll") for (int m = 0; m < 4; ++m) _Pragma("unroll") for (int k = 0; k < 2; ++k) dst[m][k] = *(const PG8_LAS bf16x8*)(lds + PG8_SA(b, h) + aoff + m * 2048 + k * 1024); } while (0)
; #define PG8_LDB(dst, b, h) do { _Pragma("unroll") for (int n = 0; n < 2; ++n) _Pragma("unroll") for (int k = 0; k < 2; ++k) dst[n][k] = *(const PG8_LAS bf16x8*)(lds + PG8_SB(b, h) + boff + n * 2048 + k * 1024); } while (0)
; #define PG8_MMA(ai, bj, At, Bt) do { __builtin_amdgcn_s_setprio(1); _Pragma("unroll") for (int m = 0; m < 4; ++m) _Pragma("unroll") for (int n = 0; n < 2; ++n) _Pragma("unroll") for (int k = 0; k < 2; ++k) \
;         acc[ai][bj][m][n] = __builtin_amdgcn_mfma_f32_16x16x32_bf16(Bt[n][k], At[m][k], acc[ai][bj][m][n], 0, 0, 0); __builtin_amdgcn_s_setprio(0); } while (0)
; #define PG8_WAIT_V(n) asm volatile("s_waitcnt vmcnt(" #n ")" ::: "memory")
; #define PG8_WAIT_L(n) asm volatile("s_waitcnt lgkmcnt(" #n ")" ::: "memory")
; #define PG8_BAR __builtin_amdgcn_s_barrier()
; #define PG8_SCHED __builtin_amdgcn_sched_barrier(0)
; template <class Epi, class Sched, bool ALIGN_EPI = false, bool SP2 = false>
; __device__ __forceinline__ void gemm_phase(PG8_LAS unsigned char* lds, const Gemm g, const Sched& S, const Epi& E, const int tid) {
;     ...
;             PG8_WAIT_V(8); PG8_WAIT_L(0); PG8_BAR; PG8_MMA(1, 0, At, B0); PG8_MMA(1, 1, At, B1); PG8_BAR; PG8_SCHED;
;             PG8_LDB(B0, 1, 0); PG8_LDB(B1, 1, 1); PG8_SCHED; PG8_LDA(At, 1, 0); PG8_STAGE(PG8_SA(0, 1), a2 + hstep, voffA);
;             PG8_WAIT_V(8); PG8_WAIT_L(0); PG8_BAR; PG8_MMA(0, 0, At, B0); PG8_MMA(0, 1, At, B1); PG8_BAR; PG8_SCHED;
	v_mfma_f32_16x16x32_bf16 v[64:67], v[140:143], v[198:201], v[64:67]
	v_mfma_f32_16x16x32_bf16 v[60:63], v[166:169], v[198:201], v[60:63]
	v_mfma_f32_16x16x32_bf16 v[48:51], v[140:143], v[206:209], v[48:51]
	v_mfma_f32_16x16x32_bf16 v[44:47], v[166:169], v[206:209], v[44:47]
	v_mfma_f32_16x16x32_bf16 v[32:35], v[140:143], v[214:217], v[32:35]
	v_mfma_f32_16x16x32_bf16 v[28:31], v[166:169], v[214:217], v[28:31]
	v_mfma_f32_16x16x32_bf16 v[16:19], v[140:143], v[222:225], v[16:19]
	v_mfma_f32_16x16x32_bf16 v[12:15], v[166:169], v[222:225], v[12:15]
	v_mfma_f32_16x16x32_bf16 v[64:67], v[144:147], v[202:205], v[64:67]
	v_mfma_f32_16x16x32_bf16 v[60:63], v[170:173], v[202:205], v[60:63]
	v_mfma_f32_16x16x32_bf16 v[48:51], v[144:147], v[210:213], v[48:51]
	v_mfma_f32_16x16x32_bf16 v[44:47], v[170:173], v[210:213], v[44:47]
	v_mfma_f32_16x16x32_bf16 v[32:35], v[144:147], v[218:221], v[32:35]
	v_mfma_f32_16x16x32_bf16 v[28:31], v[170:173], v[218:221], v[28:31]
	v_mfma_f32_16x16x32_bf16 v[16:19], v[144:147], v[226:229], v[16:19]
	v_mfma_f32_16x16x32_bf16 v[12:15], v[170:173], v[226:229], v[12:15]
	s_setprio 0
	s_setprio 1
	v_mfma_f32_16x16x32_bf16 v[56:59], v[174:177], v[198:201], v[56:59]
	v_mfma_f32_16x16x32_bf16 v[52:55], v[190:193], v[198:201], v[52:55]
	v_mfma_f32_16x16x32_bf16 v[40:43], v[174:177], v[206:209], v[40:43]
	v_mfma_f32_16x16x32_bf16 v[36:39], v[190:193], v[206:209], v[36:39]
	v_mfma_f32_16x16x32_bf16 v[24:27], v[174:177], v[214:217], v[24:27]
	v_mfma_f32_16x16x32_bf16 v[20:23], v[190:193], v[214:217], v[20:23]
	v_mfma_f32_16x16x32_bf16 v[8:11], v[174:177], v[222:225], v[8:11]
	v_mfma_f32_16x16x32_bf16 v[4:7], v[190:193], v[222:225], v[4:7]
	v_mfma_f32_16x16x32_bf16 v[56:59], v[186:189], v[202:205], v[56:59]
	v_mfma_f32_16x16x32_bf16 v[52:55], v[194:197], v[202:205], v[52:55]
	v_mfma_f32_16x16x32_bf16 v[40:43], v[186:189], v[210:213], v[40:43]
	v_mfma_f32_16x16x32_bf16 v[36:39], v[194:197], v[210:213], v[36:39]
	v_mfma_f32_16x16x32_bf16 v[24:27], v[186:189], v[218:221], v[24:27]
	v_mfma_f32_16x16x32_bf16 v[20:23], v[194:197], v[218:221], v[20:23]
	v_mfma_f32_16x16x32_bf16 v[8:11], v[186:189], v[226:229], v[8:11]
	v_mfma_f32_16x16x32_bf16 v[4:7], v[194:197], v[226:229], v[4:7]
	s_setprio 0
	s_barrier
	s_add_i32 s42, 0, 0x18000
	v_add_u32_e32 v138, s42, v161
	s_add_i32 s43, 0, 0x1c000
	ds_read_b128 v[140:143], v138
	ds_read_b128 v[144:147], v138 offset:1024
	ds_read_b128 v[166:169], v138 offset:2048
	ds_read_b128 v[170:173], v138 offset:3072
	v_add_u32_e32 v138, s43, v161
	ds_read_b128 v[174:177], v138
	ds_read_b128 v[186:189], v138 offset:1024
	ds_read_b128 v[190:193], v138 offset:2048
	ds_read_b128 v[194:197], v138 offset:3072
	s_add_u32 s28, s28, 0x80000
	s_addc_u32 s29, s29, 0
	s_mov_b32 m0, s44
	v_lshl_add_u64 v[138:139], s[28:29], 0, v[150:151]
	ds_read_b128 v[198:201], v165 offset:32768
	ds_read_b128 v[202:205], v165 offset:33792
	ds_read_b128 v[206:209], v165 offset:34816
	ds_read_b128 v[210:213], v165 offset:35840
	ds_read_b128 v[214:217], v165 offset:36864
	ds_read_b128 v[218:221], v165 offset:37888
	ds_read_b128 v[222:225], v165 offset:38912
	ds_read_b128 v[226:229], v165 offset:39936
	global_load_lds_dwordx4 v[138:139], off
	v_lshl_add_u64 v[138:139], s[28:29], 0, v[148:149]
	s_mov_b32 m0, s48
	s_nop 0
	global_load_lds_dwordx4 v[138:139], off
	s_waitcnt vmcnt(8)
	s_waitcnt lgkmcnt(0)
	s_setprio 1
	s_barrier
	v_mfma_f32_16x16x32_bf16 v[134:137], v[140:143], v[198:201], v[134:137]
	v_mfma_f32_16x16x32_bf16 v[124:127], v[166:169], v[198:201], v[124:127]
	v_mfma_f32_16x16x32_bf16 v[112:115], v[140:143], v[206:209], v[112:115]
	v_mfma_f32_16x16x32_bf16 v[108:111], v[166:169], v[206:209], v[108:111]
	v_mfma_f32_16x16x32_bf16 v[96:99], v[140:143], v[214:217], v[96:99]
	v_mfma_f32_16x16x32_bf16 v[92:95], v[166:169], v[214:217], v[92:95]
	v_mfma_f32_16x16x32_bf16 v[80:83], v[140:143], v[222:225], v[80:83]
	v_mfma_f32_16x16x32_bf16 v[76:79], v[166:169], v[222:225], v[76:79]
	v_mfma_f32_16x16x32_bf16 v[136:139], v[144:147], v[202:205], v[134:137]
	v_mfma_f32_16x16x32_bf16 v[124:127], v[170:173], v[202:205], v[124:127]
	v_mfma_f32_16x16x32_bf16 v[112:115], v[144:147], v[210:213], v[112:115]
	v_mfma_f32_16x16x32_bf16 v[108:111], v[170:173], v[210:213], v[108:111]
	v_mfma_f32_16x16x32_bf16 v[96:99], v[144:147], v[218:221], v[96:99]
	v_mfma_f32_16x16x32_bf16 v[92:95], v[170:173], v[218:221], v[92:95]
	v_mfma_f32_16x16x32_bf16 v[80:83], v[144:147], v[226:229], v[80:83]
	v_mfma_f32_16x16x32_bf16 v[76:79], v[170:173], v[226:229], v[76:79]
	s_setprio 0
	s_setprio 1
	v_mfma_f32_16x16x32_bf16 v[120:123], v[174:177], v[198:201], v[120:123]
	v_mfma_f32_16x16x32_bf16 v[116:119], v[190:193], v[198:201], v[116:119]
	v_mfma_f32_16x16x32_bf16 v[104:107], v[174:177], v[206:209], v[104:107]
	v_mfma_f32_16x16x32_bf16 v[100:103], v[190:193], v[206:209], v[100:103]
	v_mfma_f32_16x16x32_bf16 v[88:91], v[174:177], v[214:217], v[88:91]
	v_mfma_f32_16x16x32_bf16 v[84:87], v[190:193], v[214:217], v[84:87]
	v_mfma_f32_16x16x32_bf16 v[72:75], v[174:177], v[222:225], v[72:75]
	v_mfma_f32_16x16x32_bf16 v[68:71], v[190:193], v[222:225], v[68:71]
	v_mfma_f32_16x16x32_bf16 v[120:123], v[186:189], v[202:205], v[120:123]
	v_mfma_f32_16x16x32_bf16 v[116:119], v[194:197], v[202:205], v[116:119]
	v_mfma_f32_16x16x32_bf16 v[104:107], v[186:189], v[210:213], v[104:107]
	v_mfma_f32_16x16x32_bf16 v[100:103], v[194:197], v[210:213], v[100:103]
	v_mfma_f32_16x16x32_bf16 v[88:91], v[186:189], v[218:221], v[88:91]
	v_mfma_f32_16x16x32_bf16 v[84:87], v[194:197], v[218:221], v[84:87]
	v_mfma_f32_16x16x32_bf16 v[72:75], v[186:189], v[226:229], v[72:75]
	v_mfma_f32_16x16x32_bf16 v[68:71], v[194:197], v[226:229], v[68:71]
	s_setprio 0
	s_barrier
; #define PG8_STAGE(bufoff, gbase, voff) do { _Pragma("unroll") for (int _i = 0; _i < 2; ++_i) \
;         __builtin_amdgcn_global_load_lds((const unsigned*)((const char*)(gbase) + (voff)[_i]), (PG8_LAS unsigned*)(lds + (bufoff) + ldsw + _i * 8192), 16, 0, 0); } while (0)
; #define PG8_LDA(dst, b, h) do { _Pragma("unroll") for (int m = 0; m < 4; ++m) _Pragma("unroll") for (int k = 0; k < 2; ++k) dst[m][k] = *(const PG8_LAS bf16x8*)(lds + PG8_SA(b, h) + aoff + m * 2048 + k * 1024); } while (0)
; #define PG8_MMA(ai, bj, At, Bt) do { __builtin_amdgcn_s_setprio(1); _Pragma("unroll") for (int m = 0; m < 4; ++m) _Pragma("unroll") for (int n = 0; n < 2; ++n) _Pragma("unroll") for (int k = 0; k < 2; ++k) \
;         acc[ai][bj][m][n] = __builtin_amdgcn_mfma_f32_16x16x32_bf16(Bt[n][k], At[m][k], acc[ai][bj][m][n], 0, 0, 0); __builtin_amdgcn_s_setprio(0); } while (0)
; #define PG8_WAIT_V(n) asm volatile("s_waitcnt vmcnt(" #n ")" ::: "memory")
; #define PG8_WAIT_L(n) asm volatile("s_waitcnt lgkmcnt(" #n ")" ::: "memory")
; #define PG8_BAR __builtin_amdgcn_s_barrier()
; #define PG8_SCHED __builtin_amdgcn_sched_barrier(0)
; template <class Epi, class Sched, bool ALIGN_EPI = false, bool SP2 = false>
; __device__ __forceinline__ void gemm_phase(PG8_LAS unsigned char* lds, const Gemm g, const Sched& S, const Epi& E, const int tid) {
;     ...
;         for (int t = 0; t < nt; t += 2) {
;     ...
;             PG8_LDA(At, 1, 1); PG8_STAGE(PG8_SB(1, 0), b3, voffB); PG8_STAGE(PG8_SB(1, 1), b3 + hstep, voffB); PG8_STAGE(PG8_SA(1, 0), a3, voffA);
;             PG8_WAIT_V(8); PG8_WAIT_L(0); PG8_BAR; PG8_MMA(1, 0, At, B0); PG8_MMA(1, 1, At, B1); PG8_BAR; PG8_SCHED;
	s_add_i32 s28, s42, s31
	v_lshl_add_u64 v[134:135], v[178:179], 0, s[46:47]
	s_mov_b32 m0, s28
	ds_read_b128 v[198:201], v165 offset:49152
	ds_read_b128 v[202:205], v165 offset:50176
	ds_read_b128 v[206:209], v165 offset:51200
	ds_read_b128 v[210:213], v165 offset:52224
	ds_read_b128 v[214:217], v165 offset:53248
	ds_read_b128 v[218:221], v165 offset:54272
	ds_read_b128 v[222:225], v165 offset:55296
	ds_read_b128 v[226:229], v165 offset:56320
	global_load_lds_dwordx4 v[134:135], off
	s_add_i32 m0, s28, 0x2000
	s_add_u32 s26, s26, 0x80080
	v_lshl_add_u64 v[134:135], v[180:181], 0, s[46:47]
	s_addc_u32 s27, s27, 0
	s_add_i32 s28, s43, s31
	global_load_lds_dwordx4 v[134:135], off
	v_lshl_add_u64 v[134:135], s[26:27], 0, v[2:3]
	s_mov_b32 m0, s28
	s_nop 0
	global_load_lds_dwordx4 v[134:135], off
	v_lshl_add_u64 v[134:135], s[26:27], 0, v[0:1]
	s_add_i32 m0, s28, 0x2000
	s_nop 0
	global_load_lds_dwordx4 v[134:135], off
	v_lshl_add_u64 v[134:135], v[182:183], 0, s[46:47]
	s_mov_b32 m0, s52
	s_nop 0
	global_load_lds_dwordx4 v[134:135], off
	v_lshl_add_u64 v[134:135], v[230:231], 0, s[46:47]
	s_mov_b32 m0, s53
	s_nop 0
	global_load_lds_dwordx4 v[134:135], off
	s_waitcnt vmcnt(8)
	s_waitcnt lgkmcnt(0)
	s_setprio 1
	s_barrier
	v_mfma_f32_16x16x32_bf16 v[64:67], v[140:143], v[198:201], v[64:67]
	v_mfma_f32_16x16x32_bf16 v[60:63], v[166:169], v[198:201], v[60:63]
	v_mfma_f32_16x16x32_bf16 v[48:51], v[140:143], v[206:209], v[48:51]
	v_mfma_f32_16x16x32_bf16 v[44:47], v[166:169], v[206:209], v[44:47]
	v_mfma_f32_16x16x32_bf16 v[32:35], v[140:143], v[214:217], v[32:35]
	v_mfma_f32_16x16x32_bf16 v[28:31], v[166:169], v[214:217], v[28:31]
	v_mfma_f32_16x16x32_bf16 v[16:19], v[140:143], v[222:225], v[16:19]
	v_mfma_f32_16x16x32_bf16 v[12:15], v[166:169], v[222:225], v[12:15]
	v_mfma_f32_16x16x32_bf16 v[64:67], v[144:147], v[202:205], v[64:67]
	v_mfma_f32_16x16x32_bf16 v[60:63], v[170:173], v[202:205], v[60:63]
	v_mfma_f32_16x16x32_bf16 v[48:51], v[144:147], v[210:213], v[48:51]
	v_mfma_f32_16x16x32_bf16 v[44:47], v[170:173], v[210:213], v[44:47]
	v_mfma_f32_16x16x32_bf16 v[32:35], v[144:147], v[218:221], v[32:35]
	v_mfma_f32_16x16x32_bf16 v[28:31], v[170:173], v[218:221], v[28:31]
	v_mfma_f32_16x16x32_bf16 v[16:19], v[144:147], v[226:229], v[16:19]
	v_mfma_f32_16x16x32_bf16 v[12:15], v[170:173], v[226:229], v[12:15]
	s_setprio 0
	s_setprio 1
	v_mfma_f32_16x16x32_bf16 v[56:59], v[174:177], v[198:201], v[56:59]
	v_mfma_f32_16x16x32_bf16 v[52:55], v[190:193], v[198:201], v[52:55]
	v_mfma_f32_16x16x32_bf16 v[40:43], v[174:177], v[206:209], v[40:43]
	v_mfma_f32_16x16x32_bf16 v[36:39], v[190:193], v[206:209], v[36:39]
	v_mfma_f32_16x16x32_bf16 v[24:27], v[174:177], v[214:217], v[24:27]
	v_mfma_f32_16x16x32_bf16 v[20:23], v[190:193], v[214:217], v[20:23]
	v_mfma_f32_16x16x32_bf16 v[8:11], v[174:177], v[222:225], v[8:11]
	v_mfma_f32_16x16x32_bf16 v[4:7], v[190:193], v[222:225], v[4:7]
	v_mfma_f32_16x16x32_bf16 v[56:59], v[186:189], v[202:205], v[56:59]
	v_mfma_f32_16x16x32_bf16 v[52:55], v[194:197], v[202:205], v[52:55]
	v_mfma_f32_16x16x32_bf16 v[40:43], v[186:189], v[210:213], v[40:43]
	v_mfma_f32_16x16x32_bf16 v[36:39], v[194:197], v[210:213], v[36:39]
	v_mfma_f32_16x16x32_bf16 v[24:27], v[186:189], v[218:221], v[24:27]
	v_mfma_f32_16x16x32_bf16 v[20:23], v[194:197], v[218:221], v[20:23]
	v_mfma_f32_16x16x32_bf16 v[8:11], v[186:189], v[226:229], v[8:11]
	v_mfma_f32_16x16x32_bf16 v[4:7], v[194:197], v[226:229], v[4:7]
	s_setprio 0
	s_barrier
	s_add_i32 s51, s51, 2
	s_add_u32 s24, s24, 0x100
	s_addc_u32 s25, s25, 0
	s_add_u32 s23, s23, 0x100
	s_addc_u32 s50, s50, 0
	s_cmp_gt_u32 s51, 29
	s_cbranch_scc1 .LBB0_269
